# GEMM K loop heads aligned to 64 bytes (s_nop fill)
# speedup vs baseline: 1.0102x; 1.0102x over previous
.Lgp_215:
	.p2alignl 6, 3212836864
.LBB0_215:
	ds_read_b128 v[144:147], v151
	ds_read_b128 v[154:157], v151 offset:1024
	ds_read_b128 v[158:161], v151 offset:2048
	ds_read_b128 v[162:165], v151 offset:3072
	ds_read_b128 v[166:169], v152
	ds_read_b128 v[170:173], v152 offset:1024
	ds_read_b128 v[174:177], v152 offset:2048
	ds_read_b128 v[178:181], v152 offset:3072
	s_add_u32 s58, s54, 0xfffc0080
	s_addc_u32 s59, s55, -1
	s_cmp_eq_u32 s90, 12
	s_cselect_b32 s61, s19, s59
	s_cselect_b32 s60, s86, s58
	s_cselect_b32 s59, s15, s89
	s_cselect_b32 s58, s87, s88
	v_lshl_add_u64 v[198:199], s[54:55], 0, v[136:137]
	s_add_i32 m0, s4, 0xc000
	ds_read_b128 v[182:185], v153
	ds_read_b128 v[186:189], v153 offset:1024
	ds_read_b128 v[190:193], v153 offset:2048
	ds_read_b128 v[194:197], v153 offset:3072
	ds_read_b128 v[202:205], v153 offset:4096
	ds_read_b128 v[206:209], v153 offset:5120
	ds_read_b128 v[210:213], v153 offset:6144
	ds_read_b128 v[214:217], v153 offset:7168
	global_load_lds_dwordx4 v[198:199], off
	v_lshl_add_u64 v[198:199], s[54:55], 0, v[138:139]
	s_add_i32 m0, s4, 0xe000
	s_nop 0
	global_load_lds_dwordx4 v[198:199], off
	s_waitcnt vmcnt(8)
	s_waitcnt lgkmcnt(0)
	s_barrier
	s_waitcnt lgkmcnt(0)
	v_mfma_f32_16x16x32_bf16 v[124:127], v[144:147], v[182:185], v[124:127]
	v_mfma_f32_16x16x32_bf16 v[120:123], v[158:161], v[182:185], v[120:123]
	v_mfma_f32_16x16x32_bf16 v[116:119], v[144:147], v[190:193], v[116:119]
	v_mfma_f32_16x16x32_bf16 v[108:111], v[158:161], v[190:193], v[108:111]
	v_mfma_f32_16x16x32_bf16 v[100:103], v[144:147], v[202:205], v[100:103]
	v_mfma_f32_16x16x32_bf16 v[92:95], v[158:161], v[202:205], v[92:95]
	v_mfma_f32_16x16x32_bf16 v[84:87], v[144:147], v[210:213], v[84:87]
	v_mfma_f32_16x16x32_bf16 v[76:79], v[158:161], v[210:213], v[76:79]
	v_mfma_f32_16x16x32_bf16 v[124:127], v[154:157], v[186:189], v[124:127]
	v_mfma_f32_16x16x32_bf16 v[120:123], v[162:165], v[186:189], v[120:123]
	v_mfma_f32_16x16x32_bf16 v[116:119], v[154:157], v[194:197], v[116:119]
	v_mfma_f32_16x16x32_bf16 v[108:111], v[162:165], v[194:197], v[108:111]
	v_mfma_f32_16x16x32_bf16 v[100:103], v[154:157], v[206:209], v[100:103]
	v_mfma_f32_16x16x32_bf16 v[92:95], v[162:165], v[206:209], v[92:95]
	v_mfma_f32_16x16x32_bf16 v[84:87], v[154:157], v[214:217], v[84:87]
	v_mfma_f32_16x16x32_bf16 v[76:79], v[162:165], v[214:217], v[76:79]
	v_mfma_f32_16x16x32_bf16 v[112:115], v[166:169], v[182:185], v[112:115]
	v_mfma_f32_16x16x32_bf16 v[104:107], v[174:177], v[182:185], v[104:107]
	v_mfma_f32_16x16x32_bf16 v[96:99], v[166:169], v[190:193], v[96:99]
	v_mfma_f32_16x16x32_bf16 v[88:91], v[174:177], v[190:193], v[88:91]
	v_mfma_f32_16x16x32_bf16 v[80:83], v[166:169], v[202:205], v[80:83]
	v_mfma_f32_16x16x32_bf16 v[72:75], v[174:177], v[202:205], v[72:75]
	v_mfma_f32_16x16x32_bf16 v[68:71], v[166:169], v[210:213], v[68:71]
	v_mfma_f32_16x16x32_bf16 v[64:67], v[174:177], v[210:213], v[64:67]
	v_mfma_f32_16x16x32_bf16 v[112:115], v[170:173], v[186:189], v[112:115]
	v_mfma_f32_16x16x32_bf16 v[104:107], v[178:181], v[186:189], v[104:107]
	v_mfma_f32_16x16x32_bf16 v[96:99], v[170:173], v[194:197], v[96:99]
	v_mfma_f32_16x16x32_bf16 v[88:91], v[178:181], v[194:197], v[88:91]
	v_mfma_f32_16x16x32_bf16 v[80:83], v[170:173], v[206:209], v[80:83]
	v_mfma_f32_16x16x32_bf16 v[72:75], v[178:181], v[206:209], v[72:75]
	v_mfma_f32_16x16x32_bf16 v[68:71], v[170:173], v[214:217], v[68:71]
	v_mfma_f32_16x16x32_bf16 v[64:67], v[178:181], v[214:217], v[64:67]
	s_barrier
	s_add_i32 s91, s17, s66
	v_lshl_add_u64 v[198:199], s[58:59], 0, v[132:133]
	s_mov_b32 m0, s91
	ds_read_b128 v[182:185], v153 offset:16384
	ds_read_b128 v[186:189], v153 offset:17408
	ds_read_b128 v[190:193], v153 offset:18432
	ds_read_b128 v[194:197], v153 offset:19456
	ds_read_b128 v[202:205], v153 offset:20480
	ds_read_b128 v[206:209], v153 offset:21504
	ds_read_b128 v[210:213], v153 offset:22528
	ds_read_b128 v[214:217], v153 offset:23552
	global_load_lds_dwordx4 v[198:199], off
	s_add_i32 m0, s91, 0x2000
	s_add_u32 s92, s58, 0x40000
	v_lshl_add_u64 v[218:219], s[58:59], 0, v[128:129]
	s_addc_u32 s93, s59, 0
	s_add_i32 s91, s80, s66
	global_load_lds_dwordx4 v[218:219], off
	v_lshl_add_u64 v[220:221], s[92:93], 0, v[132:133]
	s_mov_b32 m0, s91
	v_lshl_add_u64 v[222:223], s[60:61], 0, v[130:131]
	global_load_lds_dwordx4 v[220:221], off
	v_lshl_add_u64 v[220:221], s[92:93], 0, v[128:129]
	s_add_i32 m0, s91, 0x2000
	s_nop 0
	global_load_lds_dwordx4 v[220:221], off
	v_lshl_add_u64 v[220:221], s[60:61], 0, v[134:135]
	s_mov_b32 m0, s4
	s_nop 0
	global_load_lds_dwordx4 v[220:221], off
	s_mov_b32 m0, s67
	s_nop 0
	global_load_lds_dwordx4 v[222:223], off
	s_waitcnt vmcnt(8)
	s_waitcnt lgkmcnt(0)
	s_barrier
	s_waitcnt lgkmcnt(0)
	v_mfma_f32_16x16x32_bf16 v[60:63], v[144:147], v[182:185], v[60:63]
	v_mfma_f32_16x16x32_bf16 v[56:59], v[158:161], v[182:185], v[56:59]
	v_mfma_f32_16x16x32_bf16 v[52:55], v[144:147], v[190:193], v[52:55]
	v_mfma_f32_16x16x32_bf16 v[44:47], v[158:161], v[190:193], v[44:47]
	v_mfma_f32_16x16x32_bf16 v[36:39], v[144:147], v[202:205], v[36:39]
	v_mfma_f32_16x16x32_bf16 v[28:31], v[158:161], v[202:205], v[28:31]
	v_mfma_f32_16x16x32_bf16 v[20:23], v[144:147], v[210:213], v[20:23]
	v_mfma_f32_16x16x32_bf16 v[12:15], v[158:161], v[210:213], v[12:15]
	v_mfma_f32_16x16x32_bf16 v[60:63], v[154:157], v[186:189], v[60:63]
	v_mfma_f32_16x16x32_bf16 v[56:59], v[162:165], v[186:189], v[56:59]
	v_mfma_f32_16x16x32_bf16 v[52:55], v[154:157], v[194:197], v[52:55]
	v_mfma_f32_16x16x32_bf16 v[44:47], v[162:165], v[194:197], v[44:47]
	v_mfma_f32_16x16x32_bf16 v[36:39], v[154:157], v[206:209], v[36:39]
	v_mfma_f32_16x16x32_bf16 v[28:31], v[162:165], v[206:209], v[28:31]
	v_mfma_f32_16x16x32_bf16 v[20:23], v[154:157], v[214:217], v[20:23]
	v_mfma_f32_16x16x32_bf16 v[12:15], v[162:165], v[214:217], v[12:15]
	v_mfma_f32_16x16x32_bf16 v[48:51], v[166:169], v[182:185], v[48:51]
	v_mfma_f32_16x16x32_bf16 v[40:43], v[174:177], v[182:185], v[40:43]
	v_mfma_f32_16x16x32_bf16 v[32:35], v[166:169], v[190:193], v[32:35]
	v_mfma_f32_16x16x32_bf16 v[24:27], v[174:177], v[190:193], v[24:27]
	v_mfma_f32_16x16x32_bf16 v[16:19], v[166:169], v[202:205], v[16:19]
	v_mfma_f32_16x16x32_bf16 v[8:11], v[174:177], v[202:205], v[8:11]
	v_mfma_f32_16x16x32_bf16 v[4:7], v[166:169], v[210:213], v[4:7]
	v_mfma_f32_16x16x32_bf16 v[0:3], v[174:177], v[210:213], v[0:3]
	v_mfma_f32_16x16x32_bf16 v[48:51], v[170:173], v[186:189], v[48:51]
	v_mfma_f32_16x16x32_bf16 v[40:43], v[178:181], v[186:189], v[40:43]
	v_mfma_f32_16x16x32_bf16 v[32:35], v[170:173], v[194:197], v[32:35]
	v_mfma_f32_16x16x32_bf16 v[24:27], v[178:181], v[194:197], v[24:27]
	v_mfma_f32_16x16x32_bf16 v[16:19], v[170:173], v[206:209], v[16:19]
	v_mfma_f32_16x16x32_bf16 v[8:11], v[178:181], v[206:209], v[8:11]
	v_mfma_f32_16x16x32_bf16 v[4:7], v[170:173], v[214:217], v[4:7]
	v_mfma_f32_16x16x32_bf16 v[0:3], v[178:181], v[214:217], v[0:3]
	s_barrier
	s_add_i32 s91, 0, 0x18000
	s_add_i32 s92, 0, 0x1c000
	v_add_u32_e32 v162, s91, v149
	v_add_u32_e32 v178, s92, v149
	ds_read_b128 v[144:147], v162
	ds_read_b128 v[154:157], v162 offset:1024
	ds_read_b128 v[158:161], v162 offset:2048
	ds_read_b128 v[162:165], v162 offset:3072
	ds_read_b128 v[166:169], v178
	ds_read_b128 v[170:173], v178 offset:1024
	ds_read_b128 v[174:177], v178 offset:2048
	ds_read_b128 v[178:181], v178 offset:3072
	s_add_u32 s60, s60, 0x40000
	s_addc_u32 s61, s61, 0
	s_mov_b32 m0, s68
	v_lshl_add_u64 v[224:225], s[60:61], 0, v[134:135]
	ds_read_b128 v[182:185], v153 offset:32768
	ds_read_b128 v[186:189], v153 offset:33792
	ds_read_b128 v[190:193], v153 offset:34816
	ds_read_b128 v[194:197], v153 offset:35840
	ds_read_b128 v[202:205], v153 offset:36864
	ds_read_b128 v[206:209], v153 offset:37888
	ds_read_b128 v[210:213], v153 offset:38912
	ds_read_b128 v[214:217], v153 offset:39936
	global_load_lds_dwordx4 v[224:225], off
	v_lshl_add_u64 v[224:225], s[60:61], 0, v[130:131]
	s_mov_b32 m0, s69
	s_nop 0
	global_load_lds_dwordx4 v[224:225], off
	s_waitcnt vmcnt(8)
	s_waitcnt lgkmcnt(0)
	s_barrier
	s_waitcnt lgkmcnt(0)
	v_mfma_f32_16x16x32_bf16 v[124:127], v[144:147], v[182:185], v[124:127]
	v_mfma_f32_16x16x32_bf16 v[120:123], v[158:161], v[182:185], v[120:123]
	v_mfma_f32_16x16x32_bf16 v[116:119], v[144:147], v[190:193], v[116:119]
	v_mfma_f32_16x16x32_bf16 v[108:111], v[158:161], v[190:193], v[108:111]
	v_mfma_f32_16x16x32_bf16 v[100:103], v[144:147], v[202:205], v[100:103]
	v_mfma_f32_16x16x32_bf16 v[92:95], v[158:161], v[202:205], v[92:95]
	v_mfma_f32_16x16x32_bf16 v[84:87], v[144:147], v[210:213], v[84:87]
	v_mfma_f32_16x16x32_bf16 v[76:79], v[158:161], v[210:213], v[76:79]
	v_mfma_f32_16x16x32_bf16 v[124:127], v[154:157], v[186:189], v[124:127]
	v_mfma_f32_16x16x32_bf16 v[120:123], v[162:165], v[186:189], v[120:123]
	v_mfma_f32_16x16x32_bf16 v[116:119], v[154:157], v[194:197], v[116:119]
	v_mfma_f32_16x16x32_bf16 v[108:111], v[162:165], v[194:197], v[108:111]
	v_mfma_f32_16x16x32_bf16 v[100:103], v[154:157], v[206:209], v[100:103]
	v_mfma_f32_16x16x32_bf16 v[92:95], v[162:165], v[206:209], v[92:95]
	v_mfma_f32_16x16x32_bf16 v[84:87], v[154:157], v[214:217], v[84:87]
	v_mfma_f32_16x16x32_bf16 v[76:79], v[162:165], v[214:217], v[76:79]
	v_mfma_f32_16x16x32_bf16 v[112:115], v[166:169], v[182:185], v[112:115]
	v_mfma_f32_16x16x32_bf16 v[104:107], v[174:177], v[182:185], v[104:107]
	v_mfma_f32_16x16x32_bf16 v[96:99], v[166:169], v[190:193], v[96:99]
	v_mfma_f32_16x16x32_bf16 v[88:91], v[174:177], v[190:193], v[88:91]
	v_mfma_f32_16x16x32_bf16 v[80:83], v[166:169], v[202:205], v[80:83]
	v_mfma_f32_16x16x32_bf16 v[72:75], v[174:177], v[202:205], v[72:75]
	v_mfma_f32_16x16x32_bf16 v[68:71], v[166:169], v[210:213], v[68:71]
	v_mfma_f32_16x16x32_bf16 v[64:67], v[174:177], v[210:213], v[64:67]
	v_mfma_f32_16x16x32_bf16 v[112:115], v[170:173], v[186:189], v[112:115]
	v_mfma_f32_16x16x32_bf16 v[104:107], v[178:181], v[186:189], v[104:107]
	v_mfma_f32_16x16x32_bf16 v[96:99], v[170:173], v[194:197], v[96:99]
	v_mfma_f32_16x16x32_bf16 v[88:91], v[178:181], v[194:197], v[88:91]
	v_mfma_f32_16x16x32_bf16 v[80:83], v[170:173], v[206:209], v[80:83]
	v_mfma_f32_16x16x32_bf16 v[72:75], v[178:181], v[206:209], v[72:75]
	v_mfma_f32_16x16x32_bf16 v[68:71], v[170:173], v[214:217], v[68:71]
	v_mfma_f32_16x16x32_bf16 v[64:67], v[178:181], v[214:217], v[64:67]
	s_barrier
	s_add_i32 s60, s91, s66
	v_lshl_add_u64 v[198:199], v[198:199], 0, s[10:11]
	s_mov_b32 m0, s60
	ds_read_b128 v[182:185], v153 offset:49152
	ds_read_b128 v[186:189], v153 offset:50176
	ds_read_b128 v[190:193], v153 offset:51200
	ds_read_b128 v[194:197], v153 offset:52224
	ds_read_b128 v[202:205], v153 offset:53248
	ds_read_b128 v[206:209], v153 offset:54272
	ds_read_b128 v[210:213], v153 offset:55296
	ds_read_b128 v[214:217], v153 offset:56320
	global_load_lds_dwordx4 v[198:199], off
	s_add_i32 m0, s60, 0x2000
	s_add_u32 s58, s58, 0x40080
	v_lshl_add_u64 v[198:199], v[218:219], 0, s[10:11]
	s_addc_u32 s59, s59, 0
	s_add_i32 s60, s92, s66
	global_load_lds_dwordx4 v[198:199], off
	v_lshl_add_u64 v[198:199], s[58:59], 0, v[132:133]
	s_mov_b32 m0, s60
	s_nop 0
	global_load_lds_dwordx4 v[198:199], off
	v_lshl_add_u64 v[198:199], s[58:59], 0, v[128:129]
	s_add_i32 m0, s60, 0x2000
	s_nop 0
	global_load_lds_dwordx4 v[198:199], off
	v_lshl_add_u64 v[198:199], v[220:221], 0, s[10:11]
	s_mov_b32 m0, s72
	s_nop 0
	global_load_lds_dwordx4 v[198:199], off
	v_lshl_add_u64 v[198:199], v[222:223], 0, s[10:11]
	s_mov_b32 m0, s73
	s_nop 0
	global_load_lds_dwordx4 v[198:199], off
	s_waitcnt vmcnt(8)
	s_waitcnt lgkmcnt(0)
	s_barrier
	s_waitcnt lgkmcnt(0)
	v_mfma_f32_16x16x32_bf16 v[60:63], v[144:147], v[182:185], v[60:63]
	v_mfma_f32_16x16x32_bf16 v[56:59], v[158:161], v[182:185], v[56:59]
	v_mfma_f32_16x16x32_bf16 v[52:55], v[144:147], v[190:193], v[52:55]
	v_mfma_f32_16x16x32_bf16 v[44:47], v[158:161], v[190:193], v[44:47]
	v_mfma_f32_16x16x32_bf16 v[36:39], v[144:147], v[202:205], v[36:39]
	v_mfma_f32_16x16x32_bf16 v[28:31], v[158:161], v[202:205], v[28:31]
	v_mfma_f32_16x16x32_bf16 v[20:23], v[144:147], v[210:213], v[20:23]
	v_mfma_f32_16x16x32_bf16 v[12:15], v[158:161], v[210:213], v[12:15]
	v_mfma_f32_16x16x32_bf16 v[60:63], v[154:157], v[186:189], v[60:63]
	v_mfma_f32_16x16x32_bf16 v[56:59], v[162:165], v[186:189], v[56:59]
	v_mfma_f32_16x16x32_bf16 v[52:55], v[154:157], v[194:197], v[52:55]
	v_mfma_f32_16x16x32_bf16 v[44:47], v[162:165], v[194:197], v[44:47]
	v_mfma_f32_16x16x32_bf16 v[36:39], v[154:157], v[206:209], v[36:39]
	v_mfma_f32_16x16x32_bf16 v[28:31], v[162:165], v[206:209], v[28:31]
	v_mfma_f32_16x16x32_bf16 v[20:23], v[154:157], v[214:217], v[20:23]
	v_mfma_f32_16x16x32_bf16 v[12:15], v[162:165], v[214:217], v[12:15]
	v_mfma_f32_16x16x32_bf16 v[48:51], v[166:169], v[182:185], v[48:51]
	v_mfma_f32_16x16x32_bf16 v[40:43], v[174:177], v[182:185], v[40:43]
	v_mfma_f32_16x16x32_bf16 v[32:35], v[166:169], v[190:193], v[32:35]
	v_mfma_f32_16x16x32_bf16 v[24:27], v[174:177], v[190:193], v[24:27]
	v_mfma_f32_16x16x32_bf16 v[16:19], v[166:169], v[202:205], v[16:19]
	v_mfma_f32_16x16x32_bf16 v[8:11], v[174:177], v[202:205], v[8:11]
	v_mfma_f32_16x16x32_bf16 v[4:7], v[166:169], v[210:213], v[4:7]
	v_mfma_f32_16x16x32_bf16 v[0:3], v[174:177], v[210:213], v[0:3]
	v_mfma_f32_16x16x32_bf16 v[48:51], v[170:173], v[186:189], v[48:51]
	v_mfma_f32_16x16x32_bf16 v[40:43], v[178:181], v[186:189], v[40:43]
	v_mfma_f32_16x16x32_bf16 v[32:35], v[170:173], v[194:197], v[32:35]
	v_mfma_f32_16x16x32_bf16 v[24:27], v[178:181], v[194:197], v[24:27]
	v_mfma_f32_16x16x32_bf16 v[16:19], v[170:173], v[206:209], v[16:19]
	v_mfma_f32_16x16x32_bf16 v[8:11], v[178:181], v[206:209], v[8:11]
	v_mfma_f32_16x16x32_bf16 v[4:7], v[170:173], v[214:217], v[4:7]
	v_mfma_f32_16x16x32_bf16 v[0:3], v[178:181], v[214:217], v[0:3]
	s_barrier
	s_add_i32 s90, s90, 2
	s_add_u32 s54, s54, 0x100
	s_addc_u32 s55, s55, 0
	s_add_u32 s88, s88, 0x100
	s_addc_u32 s89, s89, 0
	s_cmp_gt_u32 s90, 13
	s_cbranch_scc0 .LBB0_215
	s_setprio 0
	s_and_b64 vcc, exec, s[12:13]
	s_cbranch_vccz .LBB0_218
	s_barrier

.LBB0_384:
	ds_read_b128 v[152:155], v149
	ds_read_b128 v[156:159], v149 offset:1024
	ds_read_b128 v[160:163], v149 offset:2048
	ds_read_b128 v[164:167], v149 offset:3072
	ds_read_b128 v[168:171], v150
	ds_read_b128 v[172:175], v150 offset:1024
	ds_read_b128 v[176:179], v150 offset:2048
	ds_read_b128 v[180:183], v150 offset:3072
	s_add_u32 s60, s58, 0xfffc0080
	s_addc_u32 s61, s59, -1
	s_cmp_eq_u32 s92, 12
	s_cselect_b32 s63, s17, s61
	s_cselect_b32 s62, s45, s60
	s_cselect_b32 s61, s35, s91
	s_cselect_b32 s60, s89, s90
	v_lshl_add_u64 v[144:145], s[58:59], 0, v[136:137]
	s_add_i32 m0, s74, 0xc000
	ds_read_b128 v[184:187], v151
	ds_read_b128 v[188:191], v151 offset:1024
	ds_read_b128 v[192:195], v151 offset:2048
	ds_read_b128 v[196:199], v151 offset:3072
	ds_read_b128 v[202:205], v151 offset:4096
	ds_read_b128 v[206:209], v151 offset:5120
	ds_read_b128 v[210:213], v151 offset:6144
	ds_read_b128 v[214:217], v151 offset:7168
	global_load_lds_dwordx4 v[144:145], off
	v_lshl_add_u64 v[144:145], s[58:59], 0, v[138:139]
	s_add_i32 m0, s74, 0xe000
	s_nop 0
	global_load_lds_dwordx4 v[144:145], off
	s_waitcnt vmcnt(8)
	s_waitcnt lgkmcnt(0)
	s_barrier
	s_waitcnt lgkmcnt(0)
	v_mfma_f32_16x16x32_bf16 v[124:127], v[152:155], v[184:187], v[124:127]
	v_mfma_f32_16x16x32_bf16 v[120:123], v[160:163], v[184:187], v[120:123]
	v_mfma_f32_16x16x32_bf16 v[116:119], v[152:155], v[192:195], v[116:119]
	v_mfma_f32_16x16x32_bf16 v[108:111], v[160:163], v[192:195], v[108:111]
	v_mfma_f32_16x16x32_bf16 v[100:103], v[152:155], v[202:205], v[100:103]
	v_mfma_f32_16x16x32_bf16 v[92:95], v[160:163], v[202:205], v[92:95]
	v_mfma_f32_16x16x32_bf16 v[84:87], v[152:155], v[210:213], v[84:87]
	v_mfma_f32_16x16x32_bf16 v[76:79], v[160:163], v[210:213], v[76:79]
	v_mfma_f32_16x16x32_bf16 v[124:127], v[156:159], v[188:191], v[124:127]
	v_mfma_f32_16x16x32_bf16 v[120:123], v[164:167], v[188:191], v[120:123]
	v_mfma_f32_16x16x32_bf16 v[116:119], v[156:159], v[196:199], v[116:119]
	v_mfma_f32_16x16x32_bf16 v[108:111], v[164:167], v[196:199], v[108:111]
	v_mfma_f32_16x16x32_bf16 v[100:103], v[156:159], v[206:209], v[100:103]
	v_mfma_f32_16x16x32_bf16 v[92:95], v[164:167], v[206:209], v[92:95]
	v_mfma_f32_16x16x32_bf16 v[84:87], v[156:159], v[214:217], v[84:87]
	v_mfma_f32_16x16x32_bf16 v[76:79], v[164:167], v[214:217], v[76:79]
	v_mfma_f32_16x16x32_bf16 v[112:115], v[168:171], v[184:187], v[112:115]
	v_mfma_f32_16x16x32_bf16 v[104:107], v[176:179], v[184:187], v[104:107]
	v_mfma_f32_16x16x32_bf16 v[96:99], v[168:171], v[192:195], v[96:99]
	v_mfma_f32_16x16x32_bf16 v[88:91], v[176:179], v[192:195], v[88:91]
	v_mfma_f32_16x16x32_bf16 v[80:83], v[168:171], v[202:205], v[80:83]
	v_mfma_f32_16x16x32_bf16 v[72:75], v[176:179], v[202:205], v[72:75]
	v_mfma_f32_16x16x32_bf16 v[68:71], v[168:171], v[210:213], v[68:71]
	v_mfma_f32_16x16x32_bf16 v[64:67], v[176:179], v[210:213], v[64:67]
	v_mfma_f32_16x16x32_bf16 v[112:115], v[172:175], v[188:191], v[112:115]
	v_mfma_f32_16x16x32_bf16 v[104:107], v[180:183], v[188:191], v[104:107]
	v_mfma_f32_16x16x32_bf16 v[96:99], v[172:175], v[196:199], v[96:99]
	v_mfma_f32_16x16x32_bf16 v[88:91], v[180:183], v[196:199], v[88:91]
	v_mfma_f32_16x16x32_bf16 v[80:83], v[172:175], v[206:209], v[80:83]
	v_mfma_f32_16x16x32_bf16 v[72:75], v[180:183], v[206:209], v[72:75]
	v_mfma_f32_16x16x32_bf16 v[68:71], v[172:175], v[214:217], v[68:71]
	v_mfma_f32_16x16x32_bf16 v[64:67], v[180:183], v[214:217], v[64:67]
	s_barrier
	s_add_i32 s93, s83, s73
	v_lshl_add_u64 v[144:145], s[60:61], 0, v[132:133]
	s_mov_b32 m0, s93
	ds_read_b128 v[184:187], v151 offset:16384
	ds_read_b128 v[188:191], v151 offset:17408
	ds_read_b128 v[192:195], v151 offset:18432
	ds_read_b128 v[196:199], v151 offset:19456
	ds_read_b128 v[202:205], v151 offset:20480
	ds_read_b128 v[206:209], v151 offset:21504
	ds_read_b128 v[210:213], v151 offset:22528
	ds_read_b128 v[214:217], v151 offset:23552
	global_load_lds_dwordx4 v[144:145], off
	s_add_i32 m0, s93, 0x2000
	s_add_u32 s94, s60, 0x40000
	v_lshl_add_u64 v[218:219], s[60:61], 0, v[128:129]
	s_addc_u32 s95, s61, 0
	s_add_i32 s93, s84, s73
	global_load_lds_dwordx4 v[218:219], off
	v_lshl_add_u64 v[220:221], s[94:95], 0, v[132:133]
	s_mov_b32 m0, s93
	v_lshl_add_u64 v[222:223], s[62:63], 0, v[130:131]
	global_load_lds_dwordx4 v[220:221], off
	v_lshl_add_u64 v[220:221], s[94:95], 0, v[128:129]
	s_add_i32 m0, s93, 0x2000
	s_nop 0
	global_load_lds_dwordx4 v[220:221], off
	v_lshl_add_u64 v[220:221], s[62:63], 0, v[134:135]
	s_mov_b32 m0, s74
	s_nop 0
	global_load_lds_dwordx4 v[220:221], off
	s_mov_b32 m0, s75
	s_nop 0
	global_load_lds_dwordx4 v[222:223], off
	s_waitcnt vmcnt(8)
	s_waitcnt lgkmcnt(0)
	s_barrier
	s_waitcnt lgkmcnt(0)
	v_mfma_f32_16x16x32_bf16 v[60:63], v[152:155], v[184:187], v[60:63]
	v_mfma_f32_16x16x32_bf16 v[56:59], v[160:163], v[184:187], v[56:59]
	v_mfma_f32_16x16x32_bf16 v[52:55], v[152:155], v[192:195], v[52:55]
	v_mfma_f32_16x16x32_bf16 v[44:47], v[160:163], v[192:195], v[44:47]
	v_mfma_f32_16x16x32_bf16 v[36:39], v[152:155], v[202:205], v[36:39]
	v_mfma_f32_16x16x32_bf16 v[28:31], v[160:163], v[202:205], v[28:31]
	v_mfma_f32_16x16x32_bf16 v[20:23], v[152:155], v[210:213], v[20:23]
	v_mfma_f32_16x16x32_bf16 v[12:15], v[160:163], v[210:213], v[12:15]
	v_mfma_f32_16x16x32_bf16 v[60:63], v[156:159], v[188:191], v[60:63]
	v_mfma_f32_16x16x32_bf16 v[56:59], v[164:167], v[188:191], v[56:59]
	v_mfma_f32_16x16x32_bf16 v[52:55], v[156:159], v[196:199], v[52:55]
	v_mfma_f32_16x16x32_bf16 v[44:47], v[164:167], v[196:199], v[44:47]
	v_mfma_f32_16x16x32_bf16 v[36:39], v[156:159], v[206:209], v[36:39]
	v_mfma_f32_16x16x32_bf16 v[28:31], v[164:167], v[206:209], v[28:31]
	v_mfma_f32_16x16x32_bf16 v[20:23], v[156:159], v[214:217], v[20:23]
	v_mfma_f32_16x16x32_bf16 v[12:15], v[164:167], v[214:217], v[12:15]
	v_mfma_f32_16x16x32_bf16 v[48:51], v[168:171], v[184:187], v[48:51]
	v_mfma_f32_16x16x32_bf16 v[40:43], v[176:179], v[184:187], v[40:43]
	v_mfma_f32_16x16x32_bf16 v[32:35], v[168:171], v[192:195], v[32:35]
	v_mfma_f32_16x16x32_bf16 v[24:27], v[176:179], v[192:195], v[24:27]
	v_mfma_f32_16x16x32_bf16 v[16:19], v[168:171], v[202:205], v[16:19]
	v_mfma_f32_16x16x32_bf16 v[8:11], v[176:179], v[202:205], v[8:11]
	v_mfma_f32_16x16x32_bf16 v[4:7], v[168:171], v[210:213], v[4:7]
	v_mfma_f32_16x16x32_bf16 v[0:3], v[176:179], v[210:213], v[0:3]
	v_mfma_f32_16x16x32_bf16 v[48:51], v[172:175], v[188:191], v[48:51]
	v_mfma_f32_16x16x32_bf16 v[40:43], v[180:183], v[188:191], v[40:43]
	v_mfma_f32_16x16x32_bf16 v[32:35], v[172:175], v[196:199], v[32:35]
	v_mfma_f32_16x16x32_bf16 v[24:27], v[180:183], v[196:199], v[24:27]
	v_mfma_f32_16x16x32_bf16 v[16:19], v[172:175], v[206:209], v[16:19]
	v_mfma_f32_16x16x32_bf16 v[8:11], v[180:183], v[206:209], v[8:11]
	v_mfma_f32_16x16x32_bf16 v[4:7], v[172:175], v[214:217], v[4:7]
	v_mfma_f32_16x16x32_bf16 v[0:3], v[180:183], v[214:217], v[0:3]
	s_barrier
	s_add_i32 s93, 0, 0x18000
	s_add_i32 s94, 0, 0x1c000
	v_add_u32_e32 v164, s93, v147
	v_add_u32_e32 v180, s94, v147
	ds_read_b128 v[152:155], v164
	ds_read_b128 v[156:159], v164 offset:1024
	ds_read_b128 v[160:163], v164 offset:2048
	ds_read_b128 v[164:167], v164 offset:3072
	ds_read_b128 v[168:171], v180
	ds_read_b128 v[172:175], v180 offset:1024
	ds_read_b128 v[176:179], v180 offset:2048
	ds_read_b128 v[180:183], v180 offset:3072
	s_add_u32 s62, s62, 0x40000
	s_addc_u32 s63, s63, 0
	s_mov_b32 m0, s76
	v_lshl_add_u64 v[224:225], s[62:63], 0, v[134:135]
	ds_read_b128 v[184:187], v151 offset:32768
	ds_read_b128 v[188:191], v151 offset:33792
	ds_read_b128 v[192:195], v151 offset:34816
	ds_read_b128 v[196:199], v151 offset:35840
	ds_read_b128 v[202:205], v151 offset:36864
	ds_read_b128 v[206:209], v151 offset:37888
	ds_read_b128 v[210:213], v151 offset:38912
	ds_read_b128 v[214:217], v151 offset:39936
	global_load_lds_dwordx4 v[224:225], off
	v_lshl_add_u64 v[224:225], s[62:63], 0, v[130:131]
	s_mov_b32 m0, s77
	s_nop 0
	global_load_lds_dwordx4 v[224:225], off
	s_waitcnt vmcnt(8)
	s_waitcnt lgkmcnt(0)
	s_barrier
	s_waitcnt lgkmcnt(0)
	v_mfma_f32_16x16x32_bf16 v[124:127], v[152:155], v[184:187], v[124:127]
	v_mfma_f32_16x16x32_bf16 v[120:123], v[160:163], v[184:187], v[120:123]
	v_mfma_f32_16x16x32_bf16 v[116:119], v[152:155], v[192:195], v[116:119]
	v_mfma_f32_16x16x32_bf16 v[108:111], v[160:163], v[192:195], v[108:111]
	v_mfma_f32_16x16x32_bf16 v[100:103], v[152:155], v[202:205], v[100:103]
	v_mfma_f32_16x16x32_bf16 v[92:95], v[160:163], v[202:205], v[92:95]
	v_mfma_f32_16x16x32_bf16 v[84:87], v[152:155], v[210:213], v[84:87]
	v_mfma_f32_16x16x32_bf16 v[76:79], v[160:163], v[210:213], v[76:79]
	v_mfma_f32_16x16x32_bf16 v[124:127], v[156:159], v[188:191], v[124:127]
	v_mfma_f32_16x16x32_bf16 v[120:123], v[164:167], v[188:191], v[120:123]
	v_mfma_f32_16x16x32_bf16 v[116:119], v[156:159], v[196:199], v[116:119]
	v_mfma_f32_16x16x32_bf16 v[108:111], v[164:167], v[196:199], v[108:111]
	v_mfma_f32_16x16x32_bf16 v[100:103], v[156:159], v[206:209], v[100:103]
	v_mfma_f32_16x16x32_bf16 v[92:95], v[164:167], v[206:209], v[92:95]
	v_mfma_f32_16x16x32_bf16 v[84:87], v[156:159], v[214:217], v[84:87]
	v_mfma_f32_16x16x32_bf16 v[76:79], v[164:167], v[214:217], v[76:79]
	v_mfma_f32_16x16x32_bf16 v[112:115], v[168:171], v[184:187], v[112:115]
	v_mfma_f32_16x16x32_bf16 v[104:107], v[176:179], v[184:187], v[104:107]
	v_mfma_f32_16x16x32_bf16 v[96:99], v[168:171], v[192:195], v[96:99]
	v_mfma_f32_16x16x32_bf16 v[88:91], v[176:179], v[192:195], v[88:91]
	v_mfma_f32_16x16x32_bf16 v[80:83], v[168:171], v[202:205], v[80:83]
	v_mfma_f32_16x16x32_bf16 v[72:75], v[176:179], v[202:205], v[72:75]
	v_mfma_f32_16x16x32_bf16 v[68:71], v[168:171], v[210:213], v[68:71]
	v_mfma_f32_16x16x32_bf16 v[64:67], v[176:179], v[210:213], v[64:67]
	v_mfma_f32_16x16x32_bf16 v[112:115], v[172:175], v[188:191], v[112:115]
	v_mfma_f32_16x16x32_bf16 v[104:107], v[180:183], v[188:191], v[104:107]
	v_mfma_f32_16x16x32_bf16 v[96:99], v[172:175], v[196:199], v[96:99]
	v_mfma_f32_16x16x32_bf16 v[88:91], v[180:183], v[196:199], v[88:91]
	v_mfma_f32_16x16x32_bf16 v[80:83], v[172:175], v[206:209], v[80:83]
	v_mfma_f32_16x16x32_bf16 v[72:75], v[180:183], v[206:209], v[72:75]
	v_mfma_f32_16x16x32_bf16 v[68:71], v[172:175], v[214:217], v[68:71]
	v_mfma_f32_16x16x32_bf16 v[64:67], v[180:183], v[214:217], v[64:67]
	s_barrier
	s_add_i32 s62, s93, s73
	v_lshl_add_u64 v[144:145], v[144:145], 0, s[10:11]
	s_mov_b32 m0, s62
	ds_read_b128 v[184:187], v151 offset:49152
	ds_read_b128 v[188:191], v151 offset:50176
	ds_read_b128 v[192:195], v151 offset:51200
	ds_read_b128 v[196:199], v151 offset:52224
	ds_read_b128 v[202:205], v151 offset:53248
	ds_read_b128 v[206:209], v151 offset:54272
	ds_read_b128 v[210:213], v151 offset:55296
	ds_read_b128 v[214:217], v151 offset:56320
	global_load_lds_dwordx4 v[144:145], off
	s_add_i32 m0, s62, 0x2000
	s_add_u32 s60, s60, 0x40080
	v_lshl_add_u64 v[144:145], v[218:219], 0, s[10:11]
	s_addc_u32 s61, s61, 0
	s_add_i32 s62, s94, s73
	global_load_lds_dwordx4 v[144:145], off
	v_lshl_add_u64 v[144:145], s[60:61], 0, v[132:133]
	s_mov_b32 m0, s62
	s_nop 0
	global_load_lds_dwordx4 v[144:145], off
	v_lshl_add_u64 v[144:145], s[60:61], 0, v[128:129]
	s_add_i32 m0, s62, 0x2000
	s_nop 0
	global_load_lds_dwordx4 v[144:145], off
	v_lshl_add_u64 v[144:145], v[220:221], 0, s[10:11]
	s_mov_b32 m0, s79
	s_nop 0
	global_load_lds_dwordx4 v[144:145], off
	v_lshl_add_u64 v[144:145], v[222:223], 0, s[10:11]
	s_mov_b32 m0, s80
	s_nop 0
	global_load_lds_dwordx4 v[144:145], off
	s_waitcnt vmcnt(8)
	s_waitcnt lgkmcnt(0)
	s_barrier
	s_waitcnt lgkmcnt(0)
	v_mfma_f32_16x16x32_bf16 v[60:63], v[152:155], v[184:187], v[60:63]
	v_mfma_f32_16x16x32_bf16 v[56:59], v[160:163], v[184:187], v[56:59]
	v_mfma_f32_16x16x32_bf16 v[52:55], v[152:155], v[192:195], v[52:55]
	v_mfma_f32_16x16x32_bf16 v[44:47], v[160:163], v[192:195], v[44:47]
	v_mfma_f32_16x16x32_bf16 v[36:39], v[152:155], v[202:205], v[36:39]
	v_mfma_f32_16x16x32_bf16 v[28:31], v[160:163], v[202:205], v[28:31]
	v_mfma_f32_16x16x32_bf16 v[20:23], v[152:155], v[210:213], v[20:23]
	v_mfma_f32_16x16x32_bf16 v[12:15], v[160:163], v[210:213], v[12:15]
	v_mfma_f32_16x16x32_bf16 v[60:63], v[156:159], v[188:191], v[60:63]
	v_mfma_f32_16x16x32_bf16 v[56:59], v[164:167], v[188:191], v[56:59]
	v_mfma_f32_16x16x32_bf16 v[52:55], v[156:159], v[196:199], v[52:55]
	v_mfma_f32_16x16x32_bf16 v[44:47], v[164:167], v[196:199], v[44:47]
	v_mfma_f32_16x16x32_bf16 v[36:39], v[156:159], v[206:209], v[36:39]
	v_mfma_f32_16x16x32_bf16 v[28:31], v[164:167], v[206:209], v[28:31]
	v_mfma_f32_16x16x32_bf16 v[20:23], v[156:159], v[214:217], v[20:23]
	v_mfma_f32_16x16x32_bf16 v[12:15], v[164:167], v[214:217], v[12:15]
	v_mfma_f32_16x16x32_bf16 v[48:51], v[168:171], v[184:187], v[48:51]
	v_mfma_f32_16x16x32_bf16 v[40:43], v[176:179], v[184:187], v[40:43]
	v_mfma_f32_16x16x32_bf16 v[32:35], v[168:171], v[192:195], v[32:35]
	v_mfma_f32_16x16x32_bf16 v[24:27], v[176:179], v[192:195], v[24:27]
	v_mfma_f32_16x16x32_bf16 v[16:19], v[168:171], v[202:205], v[16:19]
	v_mfma_f32_16x16x32_bf16 v[8:11], v[176:179], v[202:205], v[8:11]
	v_mfma_f32_16x16x32_bf16 v[4:7], v[168:171], v[210:213], v[4:7]
	v_mfma_f32_16x16x32_bf16 v[0:3], v[176:179], v[210:213], v[0:3]
	v_mfma_f32_16x16x32_bf16 v[48:51], v[172:175], v[188:191], v[48:51]
	v_mfma_f32_16x16x32_bf16 v[40:43], v[180:183], v[188:191], v[40:43]
	v_mfma_f32_16x16x32_bf16 v[32:35], v[172:175], v[196:199], v[32:35]
	v_mfma_f32_16x16x32_bf16 v[24:27], v[180:183], v[196:199], v[24:27]
	v_mfma_f32_16x16x32_bf16 v[16:19], v[172:175], v[206:209], v[16:19]
	v_mfma_f32_16x16x32_bf16 v[8:11], v[180:183], v[206:209], v[8:11]
	v_mfma_f32_16x16x32_bf16 v[4:7], v[172:175], v[214:217], v[4:7]
	v_mfma_f32_16x16x32_bf16 v[0:3], v[180:183], v[214:217], v[0:3]
	s_barrier
	s_add_i32 s92, s92, 2
	s_add_u32 s58, s58, 0x100
	s_addc_u32 s59, s59, 0
	s_add_u32 s90, s90, 0x100
	s_addc_u32 s91, s91, 0
	s_cmp_gt_u32 s92, 13
	s_cbranch_scc0 .LBB0_384
	s_setprio 0
	s_and_b64 vcc, exec, s[12:13]
	s_cbranch_vccz .LBB0_387
	s_barrier

.LBB0_729:
	ds_read_b128 v[148:151], v145
	ds_read_b128 v[152:155], v145 offset:1024
	ds_read_b128 v[156:159], v145 offset:2048
	ds_read_b128 v[160:163], v145 offset:3072
	ds_read_b128 v[164:167], v146
	ds_read_b128 v[168:171], v146 offset:1024
	ds_read_b128 v[172:175], v146 offset:2048
	ds_read_b128 v[176:179], v146 offset:3072
	s_add_u32 s60, s58, 0xfffc0080
	s_addc_u32 s61, s59, -1
	s_cmp_eq_u32 s82, 12
	s_cselect_b32 s63, s45, s61
	s_cselect_b32 s62, s78, s60
	s_cselect_b32 s61, s35, s81
	s_cselect_b32 s60, s79, s80
	v_lshl_add_u64 v[140:141], s[58:59], 0, v[132:133]
	s_add_i32 m0, s67, 0xc000
	ds_read_b128 v[180:183], v147
	ds_read_b128 v[184:187], v147 offset:1024
	ds_read_b128 v[188:191], v147 offset:2048
	ds_read_b128 v[192:195], v147 offset:3072
	ds_read_b128 v[196:199], v147 offset:4096
	ds_read_b128 v[202:205], v147 offset:5120
	ds_read_b128 v[206:209], v147 offset:6144
	ds_read_b128 v[210:213], v147 offset:7168
	global_load_lds_dwordx4 v[140:141], off
	v_lshl_add_u64 v[140:141], s[58:59], 0, v[134:135]
	s_add_i32 m0, s67, 0xe000
	s_nop 0
	global_load_lds_dwordx4 v[140:141], off
	s_waitcnt vmcnt(8)
	s_waitcnt lgkmcnt(0)
	s_barrier
	s_waitcnt lgkmcnt(0)
	v_mfma_f32_16x16x32_bf16 v[124:127], v[148:151], v[180:183], v[124:127]
	v_mfma_f32_16x16x32_bf16 v[120:123], v[156:159], v[180:183], v[120:123]
	v_mfma_f32_16x16x32_bf16 v[112:115], v[148:151], v[188:191], v[112:115]
	v_mfma_f32_16x16x32_bf16 v[108:111], v[156:159], v[188:191], v[108:111]
	v_mfma_f32_16x16x32_bf16 v[96:99], v[148:151], v[196:199], v[96:99]
	v_mfma_f32_16x16x32_bf16 v[92:95], v[156:159], v[196:199], v[92:95]
	v_mfma_f32_16x16x32_bf16 v[80:83], v[148:151], v[206:209], v[80:83]
	v_mfma_f32_16x16x32_bf16 v[76:79], v[156:159], v[206:209], v[76:79]
	v_mfma_f32_16x16x32_bf16 v[124:127], v[152:155], v[184:187], v[124:127]
	v_mfma_f32_16x16x32_bf16 v[120:123], v[160:163], v[184:187], v[120:123]
	v_mfma_f32_16x16x32_bf16 v[112:115], v[152:155], v[192:195], v[112:115]
	v_mfma_f32_16x16x32_bf16 v[108:111], v[160:163], v[192:195], v[108:111]
	v_mfma_f32_16x16x32_bf16 v[96:99], v[152:155], v[202:205], v[96:99]
	v_mfma_f32_16x16x32_bf16 v[92:95], v[160:163], v[202:205], v[92:95]
	v_mfma_f32_16x16x32_bf16 v[80:83], v[152:155], v[210:213], v[80:83]
	v_mfma_f32_16x16x32_bf16 v[76:79], v[160:163], v[210:213], v[76:79]
	v_mfma_f32_16x16x32_bf16 v[116:119], v[164:167], v[180:183], v[116:119]
	v_mfma_f32_16x16x32_bf16 v[104:107], v[172:175], v[180:183], v[104:107]
	v_mfma_f32_16x16x32_bf16 v[100:103], v[164:167], v[188:191], v[100:103]
	v_mfma_f32_16x16x32_bf16 v[88:91], v[172:175], v[188:191], v[88:91]
	v_mfma_f32_16x16x32_bf16 v[84:87], v[164:167], v[196:199], v[84:87]
	v_mfma_f32_16x16x32_bf16 v[72:75], v[172:175], v[196:199], v[72:75]
	v_mfma_f32_16x16x32_bf16 v[68:71], v[164:167], v[206:209], v[68:71]
	v_mfma_f32_16x16x32_bf16 v[64:67], v[172:175], v[206:209], v[64:67]
	v_mfma_f32_16x16x32_bf16 v[116:119], v[168:171], v[184:187], v[116:119]
	v_mfma_f32_16x16x32_bf16 v[104:107], v[176:179], v[184:187], v[104:107]
	v_mfma_f32_16x16x32_bf16 v[100:103], v[168:171], v[192:195], v[100:103]
	v_mfma_f32_16x16x32_bf16 v[88:91], v[176:179], v[192:195], v[88:91]
	v_mfma_f32_16x16x32_bf16 v[84:87], v[168:171], v[202:205], v[84:87]
	v_mfma_f32_16x16x32_bf16 v[72:75], v[176:179], v[202:205], v[72:75]
	v_mfma_f32_16x16x32_bf16 v[68:71], v[168:171], v[210:213], v[68:71]
	v_mfma_f32_16x16x32_bf16 v[64:67], v[176:179], v[210:213], v[64:67]
	s_barrier
	s_add_i32 s83, s76, s66
	v_lshl_add_u64 v[140:141], s[60:61], 0, v[130:131]
	s_mov_b32 m0, s83
	ds_read_b128 v[180:183], v147 offset:16384
	ds_read_b128 v[184:187], v147 offset:17408
	ds_read_b128 v[188:191], v147 offset:18432
	ds_read_b128 v[192:195], v147 offset:19456
	ds_read_b128 v[196:199], v147 offset:20480
	ds_read_b128 v[202:205], v147 offset:21504
	ds_read_b128 v[206:209], v147 offset:22528
	ds_read_b128 v[210:213], v147 offset:23552
	global_load_lds_dwordx4 v[140:141], off
	s_add_i32 m0, s83, 0x2000
	s_add_u32 s84, s60, 0x40000
	v_lshl_add_u64 v[214:215], s[60:61], 0, v[128:129]
	s_addc_u32 s85, s61, 0
	s_add_i32 s83, s77, s66
	global_load_lds_dwordx4 v[214:215], off
	v_lshl_add_u64 v[216:217], s[84:85], 0, v[130:131]
	s_mov_b32 m0, s83
	v_lshl_add_u64 v[218:219], s[62:63], 0, v[128:129]
	global_load_lds_dwordx4 v[216:217], off
	v_lshl_add_u64 v[216:217], s[84:85], 0, v[128:129]
	s_add_i32 m0, s83, 0x2000
	s_nop 0
	global_load_lds_dwordx4 v[216:217], off
	v_lshl_add_u64 v[216:217], s[62:63], 0, v[130:131]
	s_mov_b32 m0, s67
	s_nop 0
	global_load_lds_dwordx4 v[216:217], off
	s_mov_b32 m0, s68
	s_nop 0
	global_load_lds_dwordx4 v[218:219], off
	s_waitcnt vmcnt(8)
	s_waitcnt lgkmcnt(0)
	s_barrier
	s_waitcnt lgkmcnt(0)
	v_mfma_f32_16x16x32_bf16 v[60:63], v[148:151], v[180:183], v[60:63]
	v_mfma_f32_16x16x32_bf16 v[56:59], v[156:159], v[180:183], v[56:59]
	v_mfma_f32_16x16x32_bf16 v[48:51], v[148:151], v[188:191], v[48:51]
	v_mfma_f32_16x16x32_bf16 v[44:47], v[156:159], v[188:191], v[44:47]
	v_mfma_f32_16x16x32_bf16 v[32:35], v[148:151], v[196:199], v[32:35]
	v_mfma_f32_16x16x32_bf16 v[28:31], v[156:159], v[196:199], v[28:31]
	v_mfma_f32_16x16x32_bf16 v[16:19], v[148:151], v[206:209], v[16:19]
	v_mfma_f32_16x16x32_bf16 v[12:15], v[156:159], v[206:209], v[12:15]
	v_mfma_f32_16x16x32_bf16 v[60:63], v[152:155], v[184:187], v[60:63]
	v_mfma_f32_16x16x32_bf16 v[56:59], v[160:163], v[184:187], v[56:59]
	v_mfma_f32_16x16x32_bf16 v[48:51], v[152:155], v[192:195], v[48:51]
	v_mfma_f32_16x16x32_bf16 v[44:47], v[160:163], v[192:195], v[44:47]
	v_mfma_f32_16x16x32_bf16 v[32:35], v[152:155], v[202:205], v[32:35]
	v_mfma_f32_16x16x32_bf16 v[28:31], v[160:163], v[202:205], v[28:31]
	v_mfma_f32_16x16x32_bf16 v[16:19], v[152:155], v[210:213], v[16:19]
	v_mfma_f32_16x16x32_bf16 v[12:15], v[160:163], v[210:213], v[12:15]
	v_mfma_f32_16x16x32_bf16 v[52:55], v[164:167], v[180:183], v[52:55]
	v_mfma_f32_16x16x32_bf16 v[40:43], v[172:175], v[180:183], v[40:43]
	v_mfma_f32_16x16x32_bf16 v[36:39], v[164:167], v[188:191], v[36:39]
	v_mfma_f32_16x16x32_bf16 v[24:27], v[172:175], v[188:191], v[24:27]
	v_mfma_f32_16x16x32_bf16 v[20:23], v[164:167], v[196:199], v[20:23]
	v_mfma_f32_16x16x32_bf16 v[8:11], v[172:175], v[196:199], v[8:11]
	v_mfma_f32_16x16x32_bf16 v[4:7], v[164:167], v[206:209], v[4:7]
	v_mfma_f32_16x16x32_bf16 v[0:3], v[172:175], v[206:209], v[0:3]
	v_mfma_f32_16x16x32_bf16 v[52:55], v[168:171], v[184:187], v[52:55]
	v_mfma_f32_16x16x32_bf16 v[40:43], v[176:179], v[184:187], v[40:43]
	v_mfma_f32_16x16x32_bf16 v[36:39], v[168:171], v[192:195], v[36:39]
	v_mfma_f32_16x16x32_bf16 v[24:27], v[176:179], v[192:195], v[24:27]
	v_mfma_f32_16x16x32_bf16 v[20:23], v[168:171], v[202:205], v[20:23]
	v_mfma_f32_16x16x32_bf16 v[8:11], v[176:179], v[202:205], v[8:11]
	v_mfma_f32_16x16x32_bf16 v[4:7], v[168:171], v[210:213], v[4:7]
	v_mfma_f32_16x16x32_bf16 v[0:3], v[176:179], v[210:213], v[0:3]
	s_barrier
	s_add_i32 s83, 0, 0x18000
	s_add_i32 s84, 0, 0x1c000
	v_add_u32_e32 v160, s83, v143
	v_add_u32_e32 v176, s84, v143
	ds_read_b128 v[148:151], v160
	ds_read_b128 v[152:155], v160 offset:1024
	ds_read_b128 v[156:159], v160 offset:2048
	ds_read_b128 v[160:163], v160 offset:3072
	ds_read_b128 v[164:167], v176
	ds_read_b128 v[168:171], v176 offset:1024
	ds_read_b128 v[172:175], v176 offset:2048
	ds_read_b128 v[176:179], v176 offset:3072
	s_add_u32 s62, s62, 0x40000
	s_addc_u32 s63, s63, 0
	s_mov_b32 m0, s69
	v_lshl_add_u64 v[220:221], s[62:63], 0, v[130:131]
	ds_read_b128 v[180:183], v147 offset:32768
	ds_read_b128 v[184:187], v147 offset:33792
	ds_read_b128 v[188:191], v147 offset:34816
	ds_read_b128 v[192:195], v147 offset:35840
	ds_read_b128 v[196:199], v147 offset:36864
	ds_read_b128 v[202:205], v147 offset:37888
	ds_read_b128 v[206:209], v147 offset:38912
	ds_read_b128 v[210:213], v147 offset:39936
	global_load_lds_dwordx4 v[220:221], off
	v_lshl_add_u64 v[220:221], s[62:63], 0, v[128:129]
	s_mov_b32 m0, s70
	s_nop 0
	global_load_lds_dwordx4 v[220:221], off
	s_waitcnt vmcnt(8)
	s_waitcnt lgkmcnt(0)
	s_barrier
	s_waitcnt lgkmcnt(0)
	v_mfma_f32_16x16x32_bf16 v[124:127], v[148:151], v[180:183], v[124:127]
	v_mfma_f32_16x16x32_bf16 v[120:123], v[156:159], v[180:183], v[120:123]
	v_mfma_f32_16x16x32_bf16 v[112:115], v[148:151], v[188:191], v[112:115]
	v_mfma_f32_16x16x32_bf16 v[108:111], v[156:159], v[188:191], v[108:111]
	v_mfma_f32_16x16x32_bf16 v[96:99], v[148:151], v[196:199], v[96:99]
	v_mfma_f32_16x16x32_bf16 v[92:95], v[156:159], v[196:199], v[92:95]
	v_mfma_f32_16x16x32_bf16 v[80:83], v[148:151], v[206:209], v[80:83]
	v_mfma_f32_16x16x32_bf16 v[76:79], v[156:159], v[206:209], v[76:79]
	v_mfma_f32_16x16x32_bf16 v[124:127], v[152:155], v[184:187], v[124:127]
	v_mfma_f32_16x16x32_bf16 v[120:123], v[160:163], v[184:187], v[120:123]
	v_mfma_f32_16x16x32_bf16 v[112:115], v[152:155], v[192:195], v[112:115]
	v_mfma_f32_16x16x32_bf16 v[108:111], v[160:163], v[192:195], v[108:111]
	v_mfma_f32_16x16x32_bf16 v[96:99], v[152:155], v[202:205], v[96:99]
	v_mfma_f32_16x16x32_bf16 v[92:95], v[160:163], v[202:205], v[92:95]
	v_mfma_f32_16x16x32_bf16 v[80:83], v[152:155], v[210:213], v[80:83]
	v_mfma_f32_16x16x32_bf16 v[76:79], v[160:163], v[210:213], v[76:79]
	v_mfma_f32_16x16x32_bf16 v[116:119], v[164:167], v[180:183], v[116:119]
	v_mfma_f32_16x16x32_bf16 v[104:107], v[172:175], v[180:183], v[104:107]
	v_mfma_f32_16x16x32_bf16 v[100:103], v[164:167], v[188:191], v[100:103]
	v_mfma_f32_16x16x32_bf16 v[88:91], v[172:175], v[188:191], v[88:91]
	v_mfma_f32_16x16x32_bf16 v[84:87], v[164:167], v[196:199], v[84:87]
	v_mfma_f32_16x16x32_bf16 v[72:75], v[172:175], v[196:199], v[72:75]
	v_mfma_f32_16x16x32_bf16 v[68:71], v[164:167], v[206:209], v[68:71]
	v_mfma_f32_16x16x32_bf16 v[64:67], v[172:175], v[206:209], v[64:67]
	v_mfma_f32_16x16x32_bf16 v[116:119], v[168:171], v[184:187], v[116:119]
	v_mfma_f32_16x16x32_bf16 v[104:107], v[176:179], v[184:187], v[104:107]
	v_mfma_f32_16x16x32_bf16 v[100:103], v[168:171], v[192:195], v[100:103]
	v_mfma_f32_16x16x32_bf16 v[88:91], v[176:179], v[192:195], v[88:91]
	v_mfma_f32_16x16x32_bf16 v[84:87], v[168:171], v[202:205], v[84:87]
	v_mfma_f32_16x16x32_bf16 v[72:75], v[176:179], v[202:205], v[72:75]
	v_mfma_f32_16x16x32_bf16 v[68:71], v[168:171], v[210:213], v[68:71]
	v_mfma_f32_16x16x32_bf16 v[64:67], v[176:179], v[210:213], v[64:67]
	s_barrier
	s_add_i32 s62, s83, s66
	v_lshl_add_u64 v[140:141], v[140:141], 0, s[6:7]
	s_mov_b32 m0, s62
	ds_read_b128 v[180:183], v147 offset:49152
	ds_read_b128 v[184:187], v147 offset:50176
	ds_read_b128 v[188:191], v147 offset:51200
	ds_read_b128 v[192:195], v147 offset:52224
	ds_read_b128 v[196:199], v147 offset:53248
	ds_read_b128 v[202:205], v147 offset:54272
	ds_read_b128 v[206:209], v147 offset:55296
	ds_read_b128 v[210:213], v147 offset:56320
	global_load_lds_dwordx4 v[140:141], off
	s_add_i32 m0, s62, 0x2000
	s_add_u32 s60, s60, 0x40080
	v_lshl_add_u64 v[140:141], v[214:215], 0, s[6:7]
	s_addc_u32 s61, s61, 0
	s_add_i32 s62, s84, s66
	global_load_lds_dwordx4 v[140:141], off
	v_lshl_add_u64 v[140:141], s[60:61], 0, v[130:131]
	s_mov_b32 m0, s62
	s_nop 0
	global_load_lds_dwordx4 v[140:141], off
	v_lshl_add_u64 v[140:141], s[60:61], 0, v[128:129]
	s_add_i32 m0, s62, 0x2000
	s_nop 0
	global_load_lds_dwordx4 v[140:141], off
	v_lshl_add_u64 v[140:141], v[216:217], 0, s[6:7]
	s_mov_b32 m0, s72
	s_nop 0
	global_load_lds_dwordx4 v[140:141], off
	v_lshl_add_u64 v[140:141], v[218:219], 0, s[6:7]
	s_mov_b32 m0, s73
	s_nop 0
	global_load_lds_dwordx4 v[140:141], off
	s_waitcnt vmcnt(8)
	s_waitcnt lgkmcnt(0)
	s_barrier
	s_waitcnt lgkmcnt(0)
	v_mfma_f32_16x16x32_bf16 v[60:63], v[148:151], v[180:183], v[60:63]
	v_mfma_f32_16x16x32_bf16 v[56:59], v[156:159], v[180:183], v[56:59]
	v_mfma_f32_16x16x32_bf16 v[48:51], v[148:151], v[188:191], v[48:51]
	v_mfma_f32_16x16x32_bf16 v[44:47], v[156:159], v[188:191], v[44:47]
	v_mfma_f32_16x16x32_bf16 v[32:35], v[148:151], v[196:199], v[32:35]
	v_mfma_f32_16x16x32_bf16 v[28:31], v[156:159], v[196:199], v[28:31]
	v_mfma_f32_16x16x32_bf16 v[16:19], v[148:151], v[206:209], v[16:19]
	v_mfma_f32_16x16x32_bf16 v[12:15], v[156:159], v[206:209], v[12:15]
	v_mfma_f32_16x16x32_bf16 v[60:63], v[152:155], v[184:187], v[60:63]
	v_mfma_f32_16x16x32_bf16 v[56:59], v[160:163], v[184:187], v[56:59]
	v_mfma_f32_16x16x32_bf16 v[48:51], v[152:155], v[192:195], v[48:51]
	v_mfma_f32_16x16x32_bf16 v[44:47], v[160:163], v[192:195], v[44:47]
	v_mfma_f32_16x16x32_bf16 v[32:35], v[152:155], v[202:205], v[32:35]
	v_mfma_f32_16x16x32_bf16 v[28:31], v[160:163], v[202:205], v[28:31]
	v_mfma_f32_16x16x32_bf16 v[16:19], v[152:155], v[210:213], v[16:19]
	v_mfma_f32_16x16x32_bf16 v[12:15], v[160:163], v[210:213], v[12:15]
	v_mfma_f32_16x16x32_bf16 v[52:55], v[164:167], v[180:183], v[52:55]
	v_mfma_f32_16x16x32_bf16 v[40:43], v[172:175], v[180:183], v[40:43]
	v_mfma_f32_16x16x32_bf16 v[36:39], v[164:167], v[188:191], v[36:39]
	v_mfma_f32_16x16x32_bf16 v[24:27], v[172:175], v[188:191], v[24:27]
	v_mfma_f32_16x16x32_bf16 v[20:23], v[164:167], v[196:199], v[20:23]
	v_mfma_f32_16x16x32_bf16 v[8:11], v[172:175], v[196:199], v[8:11]
	v_mfma_f32_16x16x32_bf16 v[4:7], v[164:167], v[206:209], v[4:7]
	v_mfma_f32_16x16x32_bf16 v[0:3], v[172:175], v[206:209], v[0:3]
	v_mfma_f32_16x16x32_bf16 v[52:55], v[168:171], v[184:187], v[52:55]
	v_mfma_f32_16x16x32_bf16 v[40:43], v[176:179], v[184:187], v[40:43]
	v_mfma_f32_16x16x32_bf16 v[36:39], v[168:171], v[192:195], v[36:39]
	v_mfma_f32_16x16x32_bf16 v[24:27], v[176:179], v[192:195], v[24:27]
	v_mfma_f32_16x16x32_bf16 v[20:23], v[168:171], v[202:205], v[20:23]
	v_mfma_f32_16x16x32_bf16 v[8:11], v[176:179], v[202:205], v[8:11]
	v_mfma_f32_16x16x32_bf16 v[4:7], v[168:171], v[210:213], v[4:7]
	v_mfma_f32_16x16x32_bf16 v[0:3], v[176:179], v[210:213], v[0:3]
	s_barrier
	s_add_i32 s82, s82, 2
	s_add_u32 s58, s58, 0x100
	s_addc_u32 s59, s59, 0
	s_add_u32 s80, s80, 0x100
	s_addc_u32 s81, s81, 0
	s_cmp_gt_u32 s82, 13
	s_cbranch_scc0 .LBB0_729
	s_setprio 0
	s_and_b64 vcc, exec, s[8:9]
	s_cbranch_vccz .LBB0_732
	s_barrier

.LBB0_866:
	ds_read_b128 v[64:67], v203
	ds_read_b128 v[68:71], v203 offset:1024
	ds_read_b128 v[72:75], v203 offset:2048
	ds_read_b128 v[76:79], v203 offset:3072
	ds_read_b128 v[80:83], v204
	ds_read_b128 v[84:87], v204 offset:1024
	ds_read_b128 v[88:91], v204 offset:2048
	ds_read_b128 v[92:95], v204 offset:3072
	s_add_u32 s64, s62, 0xfffc0080
	s_addc_u32 s65, s63, -1
	s_cmp_eq_u32 s90, 12
	s_cselect_b32 s67, s55, s65
	s_cselect_b32 s66, s86, s64
	s_cselect_b32 s65, s53, s89
	s_cselect_b32 s64, s87, s88
	v_lshl_add_u64 v[220:221], s[62:63], 0, v[172:173]
	s_add_i32 m0, s73, 0xc000
	ds_read_b128 v[180:183], v205
	ds_read_b128 v[184:187], v205 offset:1024
	ds_read_b128 v[188:191], v205 offset:2048
	ds_read_b128 v[192:195], v205 offset:3072
	ds_read_b128 v[196:199], v205 offset:4096
	ds_read_b128 v[208:211], v205 offset:5120
	ds_read_b128 v[212:215], v205 offset:6144
	ds_read_b128 v[216:219], v205 offset:7168
	global_load_lds_dwordx4 v[220:221], off
	v_lshl_add_u64 v[220:221], s[62:63], 0, v[174:175]
	s_add_i32 m0, s73, 0xe000
	s_nop 0
	global_load_lds_dwordx4 v[220:221], off
	s_waitcnt vmcnt(8)
	s_waitcnt lgkmcnt(0)
	s_barrier
	s_waitcnt lgkmcnt(0)
	v_mfma_f32_16x16x32_bf16 v[148:151], v[64:67], v[180:183], v[148:151]
	v_mfma_f32_16x16x32_bf16 v[144:147], v[72:75], v[180:183], v[144:147]
	v_mfma_f32_16x16x32_bf16 v[132:135], v[64:67], v[188:191], v[132:135]
	v_mfma_f32_16x16x32_bf16 v[128:131], v[72:75], v[188:191], v[128:131]
	v_mfma_f32_16x16x32_bf16 v[116:119], v[64:67], v[196:199], v[116:119]
	v_mfma_f32_16x16x32_bf16 v[112:115], v[72:75], v[196:199], v[112:115]
	v_mfma_f32_16x16x32_bf16 v[104:107], v[64:67], v[212:215], v[104:107]
	v_mfma_f32_16x16x32_bf16 v[100:103], v[72:75], v[212:215], v[100:103]
	v_mfma_f32_16x16x32_bf16 v[148:151], v[68:71], v[184:187], v[148:151]
	v_mfma_f32_16x16x32_bf16 v[144:147], v[76:79], v[184:187], v[144:147]
	v_mfma_f32_16x16x32_bf16 v[132:135], v[68:71], v[192:195], v[132:135]
	v_mfma_f32_16x16x32_bf16 v[128:131], v[76:79], v[192:195], v[128:131]
	v_mfma_f32_16x16x32_bf16 v[116:119], v[68:71], v[208:211], v[116:119]
	v_mfma_f32_16x16x32_bf16 v[112:115], v[76:79], v[208:211], v[112:115]
	v_mfma_f32_16x16x32_bf16 v[104:107], v[68:71], v[216:219], v[104:107]
	v_mfma_f32_16x16x32_bf16 v[100:103], v[76:79], v[216:219], v[100:103]
	v_mfma_f32_16x16x32_bf16 v[152:155], v[80:83], v[180:183], v[152:155]
	v_mfma_f32_16x16x32_bf16 v[156:159], v[88:91], v[180:183], v[156:159]
	v_mfma_f32_16x16x32_bf16 v[136:139], v[80:83], v[188:191], v[136:139]
	v_mfma_f32_16x16x32_bf16 v[140:143], v[88:91], v[188:191], v[140:143]
	v_mfma_f32_16x16x32_bf16 v[120:123], v[80:83], v[196:199], v[120:123]
	v_mfma_f32_16x16x32_bf16 v[124:127], v[88:91], v[196:199], v[124:127]
	v_mfma_f32_16x16x32_bf16 v[96:99], v[80:83], v[212:215], v[96:99]
	v_mfma_f32_16x16x32_bf16 v[108:111], v[88:91], v[212:215], v[108:111]
	v_mfma_f32_16x16x32_bf16 v[152:155], v[84:87], v[184:187], v[152:155]
	v_mfma_f32_16x16x32_bf16 v[156:159], v[92:95], v[184:187], v[156:159]
	v_mfma_f32_16x16x32_bf16 v[136:139], v[84:87], v[192:195], v[136:139]
	v_mfma_f32_16x16x32_bf16 v[140:143], v[92:95], v[192:195], v[140:143]
	v_mfma_f32_16x16x32_bf16 v[120:123], v[84:87], v[208:211], v[120:123]
	v_mfma_f32_16x16x32_bf16 v[124:127], v[92:95], v[208:211], v[124:127]
	v_mfma_f32_16x16x32_bf16 v[96:99], v[84:87], v[216:219], v[96:99]
	v_mfma_f32_16x16x32_bf16 v[108:111], v[92:95], v[216:219], v[108:111]
	s_barrier
	s_add_i32 s91, s82, s72
	v_lshl_add_u64 v[220:221], s[64:65], 0, v[164:165]
	s_mov_b32 m0, s91
	ds_read_b128 v[180:183], v205 offset:16384
	ds_read_b128 v[184:187], v205 offset:17408
	ds_read_b128 v[188:191], v205 offset:18432
	ds_read_b128 v[192:195], v205 offset:19456
	ds_read_b128 v[196:199], v205 offset:20480
	ds_read_b128 v[208:211], v205 offset:21504
	ds_read_b128 v[212:215], v205 offset:22528
	ds_read_b128 v[216:219], v205 offset:23552
	global_load_lds_dwordx4 v[220:221], off
	s_add_i32 m0, s91, 0x2000
	s_add_u32 s92, s64, 0x40000
	v_lshl_add_u64 v[222:223], s[64:65], 0, v[160:161]
	s_addc_u32 s93, s65, 0
	s_add_i32 s91, s83, s72
	global_load_lds_dwordx4 v[222:223], off
	v_lshl_add_u64 v[224:225], s[92:93], 0, v[164:165]
	s_mov_b32 m0, s91
	v_lshl_add_u64 v[226:227], s[66:67], 0, v[162:163]
	global_load_lds_dwordx4 v[224:225], off
	v_lshl_add_u64 v[224:225], s[92:93], 0, v[160:161]
	s_add_i32 m0, s91, 0x2000
	s_nop 0
	global_load_lds_dwordx4 v[224:225], off
	v_lshl_add_u64 v[224:225], s[66:67], 0, v[166:167]
	s_mov_b32 m0, s73
	s_nop 0
	global_load_lds_dwordx4 v[224:225], off
	s_mov_b32 m0, s74
	s_nop 0
	global_load_lds_dwordx4 v[226:227], off
	s_waitcnt vmcnt(8)
	s_waitcnt lgkmcnt(0)
	s_barrier
	s_waitcnt lgkmcnt(0)
	v_mfma_f32_16x16x32_bf16 v[52:55], v[64:67], v[180:183], v[52:55]
	v_mfma_f32_16x16x32_bf16 v[48:51], v[72:75], v[180:183], v[48:51]
	v_mfma_f32_16x16x32_bf16 v[36:39], v[64:67], v[188:191], v[36:39]
	v_mfma_f32_16x16x32_bf16 v[32:35], v[72:75], v[188:191], v[32:35]
	v_mfma_f32_16x16x32_bf16 v[20:23], v[64:67], v[196:199], v[20:23]
	v_mfma_f32_16x16x32_bf16 v[16:19], v[72:75], v[196:199], v[16:19]
	v_mfma_f32_16x16x32_bf16 v[8:11], v[64:67], v[212:215], v[8:11]
	v_mfma_f32_16x16x32_bf16 v[4:7], v[72:75], v[212:215], v[4:7]
	v_mfma_f32_16x16x32_bf16 v[52:55], v[68:71], v[184:187], v[52:55]
	v_mfma_f32_16x16x32_bf16 v[48:51], v[76:79], v[184:187], v[48:51]
	v_mfma_f32_16x16x32_bf16 v[36:39], v[68:71], v[192:195], v[36:39]
	v_mfma_f32_16x16x32_bf16 v[32:35], v[76:79], v[192:195], v[32:35]
	v_mfma_f32_16x16x32_bf16 v[20:23], v[68:71], v[208:211], v[20:23]
	v_mfma_f32_16x16x32_bf16 v[16:19], v[76:79], v[208:211], v[16:19]
	v_mfma_f32_16x16x32_bf16 v[8:11], v[68:71], v[216:219], v[8:11]
	v_mfma_f32_16x16x32_bf16 v[4:7], v[76:79], v[216:219], v[4:7]
	v_mfma_f32_16x16x32_bf16 v[56:59], v[80:83], v[180:183], v[56:59]
	v_mfma_f32_16x16x32_bf16 v[60:63], v[88:91], v[180:183], v[60:63]
	v_mfma_f32_16x16x32_bf16 v[40:43], v[80:83], v[188:191], v[40:43]
	v_mfma_f32_16x16x32_bf16 v[44:47], v[88:91], v[188:191], v[44:47]
	v_mfma_f32_16x16x32_bf16 v[24:27], v[80:83], v[196:199], v[24:27]
	v_mfma_f32_16x16x32_bf16 v[28:31], v[88:91], v[196:199], v[28:31]
	v_mfma_f32_16x16x32_bf16 v[0:3], v[80:83], v[212:215], v[0:3]
	v_mfma_f32_16x16x32_bf16 v[12:15], v[88:91], v[212:215], v[12:15]
	v_mfma_f32_16x16x32_bf16 v[56:59], v[84:87], v[184:187], v[56:59]
	v_mfma_f32_16x16x32_bf16 v[60:63], v[92:95], v[184:187], v[60:63]
	v_mfma_f32_16x16x32_bf16 v[40:43], v[84:87], v[192:195], v[40:43]
	v_mfma_f32_16x16x32_bf16 v[44:47], v[92:95], v[192:195], v[44:47]
	v_mfma_f32_16x16x32_bf16 v[24:27], v[84:87], v[208:211], v[24:27]
	v_mfma_f32_16x16x32_bf16 v[28:31], v[92:95], v[208:211], v[28:31]
	v_mfma_f32_16x16x32_bf16 v[0:3], v[84:87], v[216:219], v[0:3]
	v_mfma_f32_16x16x32_bf16 v[12:15], v[92:95], v[216:219], v[12:15]
	s_barrier
	s_add_i32 s91, 0, 0x18000
	s_add_i32 s92, 0, 0x1c000
	v_add_u32_e32 v76, s91, v201
	v_add_u32_e32 v92, s92, v201
	ds_read_b128 v[64:67], v76
	ds_read_b128 v[68:71], v76 offset:1024
	ds_read_b128 v[72:75], v76 offset:2048
	ds_read_b128 v[76:79], v76 offset:3072
	ds_read_b128 v[80:83], v92
	ds_read_b128 v[84:87], v92 offset:1024
	ds_read_b128 v[88:91], v92 offset:2048
	ds_read_b128 v[92:95], v92 offset:3072
	s_add_u32 s66, s66, 0x40000
	s_addc_u32 s67, s67, 0
	s_mov_b32 m0, s75
	v_lshl_add_u64 v[228:229], s[66:67], 0, v[166:167]
	ds_read_b128 v[180:183], v205 offset:32768
	ds_read_b128 v[184:187], v205 offset:33792
	ds_read_b128 v[188:191], v205 offset:34816
	ds_read_b128 v[192:195], v205 offset:35840
	ds_read_b128 v[196:199], v205 offset:36864
	ds_read_b128 v[208:211], v205 offset:37888
	ds_read_b128 v[212:215], v205 offset:38912
	ds_read_b128 v[216:219], v205 offset:39936
	global_load_lds_dwordx4 v[228:229], off
	v_lshl_add_u64 v[228:229], s[66:67], 0, v[162:163]
	s_mov_b32 m0, s76
	s_nop 0
	global_load_lds_dwordx4 v[228:229], off
	s_waitcnt vmcnt(8)
	s_waitcnt lgkmcnt(0)
	s_barrier
	s_waitcnt lgkmcnt(0)
	v_mfma_f32_16x16x32_bf16 v[148:151], v[64:67], v[180:183], v[148:151]
	v_mfma_f32_16x16x32_bf16 v[144:147], v[72:75], v[180:183], v[144:147]
	v_mfma_f32_16x16x32_bf16 v[132:135], v[64:67], v[188:191], v[132:135]
	v_mfma_f32_16x16x32_bf16 v[128:131], v[72:75], v[188:191], v[128:131]
	v_mfma_f32_16x16x32_bf16 v[116:119], v[64:67], v[196:199], v[116:119]
	v_mfma_f32_16x16x32_bf16 v[112:115], v[72:75], v[196:199], v[112:115]
	v_mfma_f32_16x16x32_bf16 v[104:107], v[64:67], v[212:215], v[104:107]
	v_mfma_f32_16x16x32_bf16 v[100:103], v[72:75], v[212:215], v[100:103]
	v_mfma_f32_16x16x32_bf16 v[148:151], v[68:71], v[184:187], v[148:151]
	v_mfma_f32_16x16x32_bf16 v[144:147], v[76:79], v[184:187], v[144:147]
	v_mfma_f32_16x16x32_bf16 v[132:135], v[68:71], v[192:195], v[132:135]
	v_mfma_f32_16x16x32_bf16 v[128:131], v[76:79], v[192:195], v[128:131]
	v_mfma_f32_16x16x32_bf16 v[116:119], v[68:71], v[208:211], v[116:119]
	v_mfma_f32_16x16x32_bf16 v[112:115], v[76:79], v[208:211], v[112:115]
	v_mfma_f32_16x16x32_bf16 v[104:107], v[68:71], v[216:219], v[104:107]
	v_mfma_f32_16x16x32_bf16 v[100:103], v[76:79], v[216:219], v[100:103]
	v_mfma_f32_16x16x32_bf16 v[152:155], v[80:83], v[180:183], v[152:155]
	v_mfma_f32_16x16x32_bf16 v[156:159], v[88:91], v[180:183], v[156:159]
	v_mfma_f32_16x16x32_bf16 v[136:139], v[80:83], v[188:191], v[136:139]
	v_mfma_f32_16x16x32_bf16 v[140:143], v[88:91], v[188:191], v[140:143]
	v_mfma_f32_16x16x32_bf16 v[120:123], v[80:83], v[196:199], v[120:123]
	v_mfma_f32_16x16x32_bf16 v[124:127], v[88:91], v[196:199], v[124:127]
	v_mfma_f32_16x16x32_bf16 v[96:99], v[80:83], v[212:215], v[96:99]
	v_mfma_f32_16x16x32_bf16 v[108:111], v[88:91], v[212:215], v[108:111]
	v_mfma_f32_16x16x32_bf16 v[152:155], v[84:87], v[184:187], v[152:155]
	v_mfma_f32_16x16x32_bf16 v[156:159], v[92:95], v[184:187], v[156:159]
	v_mfma_f32_16x16x32_bf16 v[136:139], v[84:87], v[192:195], v[136:139]
	v_mfma_f32_16x16x32_bf16 v[140:143], v[92:95], v[192:195], v[140:143]
	v_mfma_f32_16x16x32_bf16 v[120:123], v[84:87], v[208:211], v[120:123]
	v_mfma_f32_16x16x32_bf16 v[124:127], v[92:95], v[208:211], v[124:127]
	v_mfma_f32_16x16x32_bf16 v[96:99], v[84:87], v[216:219], v[96:99]
	v_mfma_f32_16x16x32_bf16 v[108:111], v[92:95], v[216:219], v[108:111]
	s_barrier
	s_add_i32 s66, s91, s72
	v_lshl_add_u64 v[220:221], v[220:221], 0, s[20:21]
	s_mov_b32 m0, s66
	ds_read_b128 v[180:183], v205 offset:49152
	ds_read_b128 v[184:187], v205 offset:50176
	ds_read_b128 v[188:191], v205 offset:51200
	ds_read_b128 v[192:195], v205 offset:52224
	ds_read_b128 v[196:199], v205 offset:53248
	ds_read_b128 v[208:211], v205 offset:54272
	ds_read_b128 v[212:215], v205 offset:55296
	ds_read_b128 v[216:219], v205 offset:56320
	global_load_lds_dwordx4 v[220:221], off
	s_add_i32 m0, s66, 0x2000
	s_add_u32 s64, s64, 0x40080
	v_lshl_add_u64 v[220:221], v[222:223], 0, s[20:21]
	s_addc_u32 s65, s65, 0
	s_add_i32 s66, s92, s72
	global_load_lds_dwordx4 v[220:221], off
	v_lshl_add_u64 v[220:221], s[64:65], 0, v[164:165]
	s_mov_b32 m0, s66
	s_nop 0
	global_load_lds_dwordx4 v[220:221], off
	v_lshl_add_u64 v[220:221], s[64:65], 0, v[160:161]
	s_add_i32 m0, s66, 0x2000
	s_nop 0
	global_load_lds_dwordx4 v[220:221], off
	v_lshl_add_u64 v[220:221], v[224:225], 0, s[20:21]
	s_mov_b32 m0, s78
	s_nop 0
	global_load_lds_dwordx4 v[220:221], off
	v_lshl_add_u64 v[220:221], v[226:227], 0, s[20:21]
	s_mov_b32 m0, s79
	s_nop 0
	global_load_lds_dwordx4 v[220:221], off
	s_waitcnt vmcnt(8)
	s_waitcnt lgkmcnt(0)
	s_barrier
	s_waitcnt lgkmcnt(0)
	v_mfma_f32_16x16x32_bf16 v[52:55], v[64:67], v[180:183], v[52:55]
	v_mfma_f32_16x16x32_bf16 v[48:51], v[72:75], v[180:183], v[48:51]
	v_mfma_f32_16x16x32_bf16 v[36:39], v[64:67], v[188:191], v[36:39]
	v_mfma_f32_16x16x32_bf16 v[32:35], v[72:75], v[188:191], v[32:35]
	v_mfma_f32_16x16x32_bf16 v[20:23], v[64:67], v[196:199], v[20:23]
	v_mfma_f32_16x16x32_bf16 v[16:19], v[72:75], v[196:199], v[16:19]
	v_mfma_f32_16x16x32_bf16 v[8:11], v[64:67], v[212:215], v[8:11]
	v_mfma_f32_16x16x32_bf16 v[4:7], v[72:75], v[212:215], v[4:7]
	v_mfma_f32_16x16x32_bf16 v[52:55], v[68:71], v[184:187], v[52:55]
	v_mfma_f32_16x16x32_bf16 v[48:51], v[76:79], v[184:187], v[48:51]
	v_mfma_f32_16x16x32_bf16 v[36:39], v[68:71], v[192:195], v[36:39]
	v_mfma_f32_16x16x32_bf16 v[32:35], v[76:79], v[192:195], v[32:35]
	v_mfma_f32_16x16x32_bf16 v[20:23], v[68:71], v[208:211], v[20:23]
	v_mfma_f32_16x16x32_bf16 v[16:19], v[76:79], v[208:211], v[16:19]
	v_mfma_f32_16x16x32_bf16 v[8:11], v[68:71], v[216:219], v[8:11]
	v_mfma_f32_16x16x32_bf16 v[4:7], v[76:79], v[216:219], v[4:7]
	v_mfma_f32_16x16x32_bf16 v[56:59], v[80:83], v[180:183], v[56:59]
	v_mfma_f32_16x16x32_bf16 v[60:63], v[88:91], v[180:183], v[60:63]
	v_mfma_f32_16x16x32_bf16 v[40:43], v[80:83], v[188:191], v[40:43]
	v_mfma_f32_16x16x32_bf16 v[44:47], v[88:91], v[188:191], v[44:47]
	v_mfma_f32_16x16x32_bf16 v[24:27], v[80:83], v[196:199], v[24:27]
	v_mfma_f32_16x16x32_bf16 v[28:31], v[88:91], v[196:199], v[28:31]
	v_mfma_f32_16x16x32_bf16 v[0:3], v[80:83], v[212:215], v[0:3]
	v_mfma_f32_16x16x32_bf16 v[12:15], v[88:91], v[212:215], v[12:15]
	v_mfma_f32_16x16x32_bf16 v[56:59], v[84:87], v[184:187], v[56:59]
	v_mfma_f32_16x16x32_bf16 v[60:63], v[92:95], v[184:187], v[60:63]
	v_mfma_f32_16x16x32_bf16 v[40:43], v[84:87], v[192:195], v[40:43]
	v_mfma_f32_16x16x32_bf16 v[44:47], v[92:95], v[192:195], v[44:47]
	v_mfma_f32_16x16x32_bf16 v[24:27], v[84:87], v[208:211], v[24:27]
	v_mfma_f32_16x16x32_bf16 v[28:31], v[92:95], v[208:211], v[28:31]
	v_mfma_f32_16x16x32_bf16 v[0:3], v[84:87], v[216:219], v[0:3]
	v_mfma_f32_16x16x32_bf16 v[12:15], v[92:95], v[216:219], v[12:15]
	s_barrier
	s_add_i32 s90, s90, 2
	s_add_u32 s62, s62, 0x100
	s_addc_u32 s63, s63, 0
	s_add_u32 s88, s88, 0x100
	s_addc_u32 s89, s89, 0
	s_cmp_gt_u32 s90, 13
	s_cbranch_scc0 .LBB0_866
	s_setprio 0
	s_and_b64 vcc, exec, s[34:35]
	s_cbranch_vccz .LBB0_869
	s_barrier

.LBB0_1018:
	ds_read_b128 v[140:143], v149
	ds_read_b128 v[152:155], v149 offset:1024
	ds_read_b128 v[156:159], v149 offset:2048
	ds_read_b128 v[160:163], v149 offset:3072
	ds_read_b128 v[164:167], v150
	ds_read_b128 v[168:171], v150 offset:1024
	ds_read_b128 v[172:175], v150 offset:2048
	ds_read_b128 v[176:179], v150 offset:3072
	s_add_u32 s54, s52, 0xfff50080
	s_addc_u32 s55, s53, -1
	s_cmp_eq_u32 s78, 40
	s_cselect_b32 s59, s5, s55
	s_cselect_b32 s58, s4, s54
	s_cselect_b32 s55, s51, s77
	s_cselect_b32 s54, s50, s76
	v_lshl_add_u64 v[144:145], s[52:53], 0, v[132:133]
	s_add_i32 m0, s63, 0xc000
	ds_read_b128 v[180:183], v151
	ds_read_b128 v[184:187], v151 offset:1024
	ds_read_b128 v[188:191], v151 offset:2048
	ds_read_b128 v[192:195], v151 offset:3072
	ds_read_b128 v[196:199], v151 offset:4096
	ds_read_b128 v[202:205], v151 offset:5120
	ds_read_b128 v[206:209], v151 offset:6144
	ds_read_b128 v[210:213], v151 offset:7168
	global_load_lds_dwordx4 v[144:145], off
	v_lshl_add_u64 v[144:145], s[52:53], 0, v[134:135]
	s_add_i32 m0, s63, 0xe000
	s_nop 0
	global_load_lds_dwordx4 v[144:145], off
	s_waitcnt vmcnt(8)
	s_waitcnt lgkmcnt(0)
	s_barrier
	s_waitcnt lgkmcnt(0)
	v_mfma_f32_16x16x32_bf16 v[124:127], v[140:143], v[180:183], v[124:127]
	v_mfma_f32_16x16x32_bf16 v[120:123], v[156:159], v[180:183], v[120:123]
	v_mfma_f32_16x16x32_bf16 v[112:115], v[140:143], v[188:191], v[112:115]
	v_mfma_f32_16x16x32_bf16 v[104:107], v[156:159], v[188:191], v[104:107]
	v_mfma_f32_16x16x32_bf16 v[96:99], v[140:143], v[196:199], v[96:99]
	v_mfma_f32_16x16x32_bf16 v[88:91], v[156:159], v[196:199], v[88:91]
	v_mfma_f32_16x16x32_bf16 v[80:83], v[140:143], v[206:209], v[80:83]
	v_mfma_f32_16x16x32_bf16 v[72:75], v[156:159], v[206:209], v[72:75]
	v_mfma_f32_16x16x32_bf16 v[124:127], v[152:155], v[184:187], v[124:127]
	v_mfma_f32_16x16x32_bf16 v[120:123], v[160:163], v[184:187], v[120:123]
	v_mfma_f32_16x16x32_bf16 v[112:115], v[152:155], v[192:195], v[112:115]
	v_mfma_f32_16x16x32_bf16 v[104:107], v[160:163], v[192:195], v[104:107]
	v_mfma_f32_16x16x32_bf16 v[96:99], v[152:155], v[202:205], v[96:99]
	v_mfma_f32_16x16x32_bf16 v[88:91], v[160:163], v[202:205], v[88:91]
	v_mfma_f32_16x16x32_bf16 v[80:83], v[152:155], v[210:213], v[80:83]
	v_mfma_f32_16x16x32_bf16 v[72:75], v[160:163], v[210:213], v[72:75]
	v_mfma_f32_16x16x32_bf16 v[116:119], v[164:167], v[180:183], v[116:119]
	v_mfma_f32_16x16x32_bf16 v[108:111], v[172:175], v[180:183], v[108:111]
	v_mfma_f32_16x16x32_bf16 v[100:103], v[164:167], v[188:191], v[100:103]
	v_mfma_f32_16x16x32_bf16 v[92:95], v[172:175], v[188:191], v[92:95]
	v_mfma_f32_16x16x32_bf16 v[84:87], v[164:167], v[196:199], v[84:87]
	v_mfma_f32_16x16x32_bf16 v[76:79], v[172:175], v[196:199], v[76:79]
	v_mfma_f32_16x16x32_bf16 v[68:71], v[164:167], v[206:209], v[68:71]
	v_mfma_f32_16x16x32_bf16 v[64:67], v[172:175], v[206:209], v[64:67]
	v_mfma_f32_16x16x32_bf16 v[116:119], v[168:171], v[184:187], v[116:119]
	v_mfma_f32_16x16x32_bf16 v[108:111], v[176:179], v[184:187], v[108:111]
	v_mfma_f32_16x16x32_bf16 v[100:103], v[168:171], v[192:195], v[100:103]
	v_mfma_f32_16x16x32_bf16 v[92:95], v[176:179], v[192:195], v[92:95]
	v_mfma_f32_16x16x32_bf16 v[84:87], v[168:171], v[202:205], v[84:87]
	v_mfma_f32_16x16x32_bf16 v[76:79], v[176:179], v[202:205], v[76:79]
	v_mfma_f32_16x16x32_bf16 v[68:71], v[168:171], v[210:213], v[68:71]
	v_mfma_f32_16x16x32_bf16 v[64:67], v[176:179], v[210:213], v[64:67]
	s_barrier
	s_add_i32 s79, s72, s62
	v_lshl_add_u64 v[144:145], s[54:55], 0, v[130:131]
	s_mov_b32 m0, s79
	ds_read_b128 v[180:183], v151 offset:16384
	ds_read_b128 v[184:187], v151 offset:17408
	ds_read_b128 v[188:191], v151 offset:18432
	ds_read_b128 v[192:195], v151 offset:19456
	ds_read_b128 v[196:199], v151 offset:20480
	ds_read_b128 v[202:205], v151 offset:21504
	ds_read_b128 v[206:209], v151 offset:22528
	ds_read_b128 v[210:213], v151 offset:23552
	global_load_lds_dwordx4 v[144:145], off
	s_add_i32 m0, s79, 0x2000
	s_add_u32 s80, s54, 0xb0000
	v_lshl_add_u64 v[214:215], s[54:55], 0, v[128:129]
	s_addc_u32 s81, s55, 0
	s_add_i32 s79, s73, s62
	global_load_lds_dwordx4 v[214:215], off
	v_lshl_add_u64 v[216:217], s[80:81], 0, v[130:131]
	s_mov_b32 m0, s79
	v_lshl_add_u64 v[218:219], s[58:59], 0, v[128:129]
	global_load_lds_dwordx4 v[216:217], off
	v_lshl_add_u64 v[216:217], s[80:81], 0, v[128:129]
	s_add_i32 m0, s79, 0x2000
	s_nop 0
	global_load_lds_dwordx4 v[216:217], off
	v_lshl_add_u64 v[216:217], s[58:59], 0, v[130:131]
	s_mov_b32 m0, s63
	s_nop 0
	global_load_lds_dwordx4 v[216:217], off
	s_mov_b32 m0, s64
	s_nop 0
	global_load_lds_dwordx4 v[218:219], off
	s_waitcnt vmcnt(8)
	s_waitcnt lgkmcnt(0)
	s_barrier
	s_waitcnt lgkmcnt(0)
	v_mfma_f32_16x16x32_bf16 v[60:63], v[140:143], v[180:183], v[60:63]
	v_mfma_f32_16x16x32_bf16 v[56:59], v[156:159], v[180:183], v[56:59]
	v_mfma_f32_16x16x32_bf16 v[48:51], v[140:143], v[188:191], v[48:51]
	v_mfma_f32_16x16x32_bf16 v[40:43], v[156:159], v[188:191], v[40:43]
	v_mfma_f32_16x16x32_bf16 v[32:35], v[140:143], v[196:199], v[32:35]
	v_mfma_f32_16x16x32_bf16 v[24:27], v[156:159], v[196:199], v[24:27]
	v_mfma_f32_16x16x32_bf16 v[16:19], v[140:143], v[206:209], v[16:19]
	v_mfma_f32_16x16x32_bf16 v[8:11], v[156:159], v[206:209], v[8:11]
	v_mfma_f32_16x16x32_bf16 v[60:63], v[152:155], v[184:187], v[60:63]
	v_mfma_f32_16x16x32_bf16 v[56:59], v[160:163], v[184:187], v[56:59]
	v_mfma_f32_16x16x32_bf16 v[48:51], v[152:155], v[192:195], v[48:51]
	v_mfma_f32_16x16x32_bf16 v[40:43], v[160:163], v[192:195], v[40:43]
	v_mfma_f32_16x16x32_bf16 v[32:35], v[152:155], v[202:205], v[32:35]
	v_mfma_f32_16x16x32_bf16 v[24:27], v[160:163], v[202:205], v[24:27]
	v_mfma_f32_16x16x32_bf16 v[16:19], v[152:155], v[210:213], v[16:19]
	v_mfma_f32_16x16x32_bf16 v[8:11], v[160:163], v[210:213], v[8:11]
	v_mfma_f32_16x16x32_bf16 v[52:55], v[164:167], v[180:183], v[52:55]
	v_mfma_f32_16x16x32_bf16 v[44:47], v[172:175], v[180:183], v[44:47]
	v_mfma_f32_16x16x32_bf16 v[36:39], v[164:167], v[188:191], v[36:39]
	v_mfma_f32_16x16x32_bf16 v[28:31], v[172:175], v[188:191], v[28:31]
	v_mfma_f32_16x16x32_bf16 v[20:23], v[164:167], v[196:199], v[20:23]
	v_mfma_f32_16x16x32_bf16 v[12:15], v[172:175], v[196:199], v[12:15]
	v_mfma_f32_16x16x32_bf16 v[4:7], v[164:167], v[206:209], v[4:7]
	v_mfma_f32_16x16x32_bf16 v[0:3], v[172:175], v[206:209], v[0:3]
	v_mfma_f32_16x16x32_bf16 v[52:55], v[168:171], v[184:187], v[52:55]
	v_mfma_f32_16x16x32_bf16 v[44:47], v[176:179], v[184:187], v[44:47]
	v_mfma_f32_16x16x32_bf16 v[36:39], v[168:171], v[192:195], v[36:39]
	v_mfma_f32_16x16x32_bf16 v[28:31], v[176:179], v[192:195], v[28:31]
	v_mfma_f32_16x16x32_bf16 v[20:23], v[168:171], v[202:205], v[20:23]
	v_mfma_f32_16x16x32_bf16 v[12:15], v[176:179], v[202:205], v[12:15]
	v_mfma_f32_16x16x32_bf16 v[4:7], v[168:171], v[210:213], v[4:7]
	v_mfma_f32_16x16x32_bf16 v[0:3], v[176:179], v[210:213], v[0:3]
	s_barrier
	s_add_i32 s79, 0, 0x18000
	s_add_i32 s80, 0, 0x1c000
	v_add_u32_e32 v160, s79, v147
	v_add_u32_e32 v176, s80, v147
	ds_read_b128 v[140:143], v160
	ds_read_b128 v[152:155], v160 offset:1024
	ds_read_b128 v[156:159], v160 offset:2048
	ds_read_b128 v[160:163], v160 offset:3072
	ds_read_b128 v[164:167], v176
	ds_read_b128 v[168:171], v176 offset:1024
	ds_read_b128 v[172:175], v176 offset:2048
	ds_read_b128 v[176:179], v176 offset:3072
	s_add_u32 s58, s58, 0xb0000
	s_addc_u32 s59, s59, 0
	s_mov_b32 m0, s65
	v_lshl_add_u64 v[220:221], s[58:59], 0, v[130:131]
	ds_read_b128 v[180:183], v151 offset:32768
	ds_read_b128 v[184:187], v151 offset:33792
	ds_read_b128 v[188:191], v151 offset:34816
	ds_read_b128 v[192:195], v151 offset:35840
	ds_read_b128 v[196:199], v151 offset:36864
	ds_read_b128 v[202:205], v151 offset:37888
	ds_read_b128 v[206:209], v151 offset:38912
	ds_read_b128 v[210:213], v151 offset:39936
	global_load_lds_dwordx4 v[220:221], off
	v_lshl_add_u64 v[220:221], s[58:59], 0, v[128:129]
	s_mov_b32 m0, s66
	s_nop 0
	global_load_lds_dwordx4 v[220:221], off
	s_waitcnt vmcnt(8)
	s_waitcnt lgkmcnt(0)
	s_barrier
	s_waitcnt lgkmcnt(0)
	v_mfma_f32_16x16x32_bf16 v[124:127], v[140:143], v[180:183], v[124:127]
	v_mfma_f32_16x16x32_bf16 v[120:123], v[156:159], v[180:183], v[120:123]
	v_mfma_f32_16x16x32_bf16 v[112:115], v[140:143], v[188:191], v[112:115]
	v_mfma_f32_16x16x32_bf16 v[104:107], v[156:159], v[188:191], v[104:107]
	v_mfma_f32_16x16x32_bf16 v[96:99], v[140:143], v[196:199], v[96:99]
	v_mfma_f32_16x16x32_bf16 v[88:91], v[156:159], v[196:199], v[88:91]
	v_mfma_f32_16x16x32_bf16 v[80:83], v[140:143], v[206:209], v[80:83]
	v_mfma_f32_16x16x32_bf16 v[72:75], v[156:159], v[206:209], v[72:75]
	v_mfma_f32_16x16x32_bf16 v[124:127], v[152:155], v[184:187], v[124:127]
	v_mfma_f32_16x16x32_bf16 v[120:123], v[160:163], v[184:187], v[120:123]
	v_mfma_f32_16x16x32_bf16 v[112:115], v[152:155], v[192:195], v[112:115]
	v_mfma_f32_16x16x32_bf16 v[104:107], v[160:163], v[192:195], v[104:107]
	v_mfma_f32_16x16x32_bf16 v[96:99], v[152:155], v[202:205], v[96:99]
	v_mfma_f32_16x16x32_bf16 v[88:91], v[160:163], v[202:205], v[88:91]
	v_mfma_f32_16x16x32_bf16 v[80:83], v[152:155], v[210:213], v[80:83]
	v_mfma_f32_16x16x32_bf16 v[72:75], v[160:163], v[210:213], v[72:75]
	v_mfma_f32_16x16x32_bf16 v[116:119], v[164:167], v[180:183], v[116:119]
	v_mfma_f32_16x16x32_bf16 v[108:111], v[172:175], v[180:183], v[108:111]
	v_mfma_f32_16x16x32_bf16 v[100:103], v[164:167], v[188:191], v[100:103]
	v_mfma_f32_16x16x32_bf16 v[92:95], v[172:175], v[188:191], v[92:95]
	v_mfma_f32_16x16x32_bf16 v[84:87], v[164:167], v[196:199], v[84:87]
	v_mfma_f32_16x16x32_bf16 v[76:79], v[172:175], v[196:199], v[76:79]
	v_mfma_f32_16x16x32_bf16 v[68:71], v[164:167], v[206:209], v[68:71]
	v_mfma_f32_16x16x32_bf16 v[64:67], v[172:175], v[206:209], v[64:67]
	v_mfma_f32_16x16x32_bf16 v[116:119], v[168:171], v[184:187], v[116:119]
	v_mfma_f32_16x16x32_bf16 v[108:111], v[176:179], v[184:187], v[108:111]
	v_mfma_f32_16x16x32_bf16 v[100:103], v[168:171], v[192:195], v[100:103]
	v_mfma_f32_16x16x32_bf16 v[92:95], v[176:179], v[192:195], v[92:95]
	v_mfma_f32_16x16x32_bf16 v[84:87], v[168:171], v[202:205], v[84:87]
	v_mfma_f32_16x16x32_bf16 v[76:79], v[176:179], v[202:205], v[76:79]
	v_mfma_f32_16x16x32_bf16 v[68:71], v[168:171], v[210:213], v[68:71]
	v_mfma_f32_16x16x32_bf16 v[64:67], v[176:179], v[210:213], v[64:67]
	s_barrier
	s_add_i32 s58, s79, s62
	v_lshl_add_u64 v[144:145], v[144:145], 0, s[10:11]
	s_mov_b32 m0, s58
	ds_read_b128 v[180:183], v151 offset:49152
	ds_read_b128 v[184:187], v151 offset:50176
	ds_read_b128 v[188:191], v151 offset:51200
	ds_read_b128 v[192:195], v151 offset:52224
	ds_read_b128 v[196:199], v151 offset:53248
	ds_read_b128 v[202:205], v151 offset:54272
	ds_read_b128 v[206:209], v151 offset:55296
	ds_read_b128 v[210:213], v151 offset:56320
	global_load_lds_dwordx4 v[144:145], off
	s_add_i32 m0, s58, 0x2000
	s_add_u32 s54, s54, 0xb0080
	v_lshl_add_u64 v[144:145], v[214:215], 0, s[10:11]
	s_addc_u32 s55, s55, 0
	s_add_i32 s58, s80, s62
	global_load_lds_dwordx4 v[144:145], off
	v_lshl_add_u64 v[144:145], s[54:55], 0, v[130:131]
	s_mov_b32 m0, s58
	s_nop 0
	global_load_lds_dwordx4 v[144:145], off
	v_lshl_add_u64 v[144:145], s[54:55], 0, v[128:129]
	s_add_i32 m0, s58, 0x2000
	s_nop 0
	global_load_lds_dwordx4 v[144:145], off
	v_lshl_add_u64 v[144:145], v[216:217], 0, s[10:11]
	s_mov_b32 m0, s68
	s_nop 0
	global_load_lds_dwordx4 v[144:145], off
	v_lshl_add_u64 v[144:145], v[218:219], 0, s[10:11]
	s_mov_b32 m0, s69
	s_nop 0
	global_load_lds_dwordx4 v[144:145], off
	s_waitcnt vmcnt(8)
	s_waitcnt lgkmcnt(0)
	s_barrier
	s_waitcnt lgkmcnt(0)
	v_mfma_f32_16x16x32_bf16 v[60:63], v[140:143], v[180:183], v[60:63]
	v_mfma_f32_16x16x32_bf16 v[56:59], v[156:159], v[180:183], v[56:59]
	v_mfma_f32_16x16x32_bf16 v[48:51], v[140:143], v[188:191], v[48:51]
	v_mfma_f32_16x16x32_bf16 v[40:43], v[156:159], v[188:191], v[40:43]
	v_mfma_f32_16x16x32_bf16 v[32:35], v[140:143], v[196:199], v[32:35]
	v_mfma_f32_16x16x32_bf16 v[24:27], v[156:159], v[196:199], v[24:27]
	v_mfma_f32_16x16x32_bf16 v[16:19], v[140:143], v[206:209], v[16:19]
	v_mfma_f32_16x16x32_bf16 v[8:11], v[156:159], v[206:209], v[8:11]
	v_mfma_f32_16x16x32_bf16 v[60:63], v[152:155], v[184:187], v[60:63]
	v_mfma_f32_16x16x32_bf16 v[56:59], v[160:163], v[184:187], v[56:59]
	v_mfma_f32_16x16x32_bf16 v[48:51], v[152:155], v[192:195], v[48:51]
	v_mfma_f32_16x16x32_bf16 v[40:43], v[160:163], v[192:195], v[40:43]
	v_mfma_f32_16x16x32_bf16 v[32:35], v[152:155], v[202:205], v[32:35]
	v_mfma_f32_16x16x32_bf16 v[24:27], v[160:163], v[202:205], v[24:27]
	v_mfma_f32_16x16x32_bf16 v[16:19], v[152:155], v[210:213], v[16:19]
	v_mfma_f32_16x16x32_bf16 v[8:11], v[160:163], v[210:213], v[8:11]
	v_mfma_f32_16x16x32_bf16 v[52:55], v[164:167], v[180:183], v[52:55]
	v_mfma_f32_16x16x32_bf16 v[44:47], v[172:175], v[180:183], v[44:47]
	v_mfma_f32_16x16x32_bf16 v[36:39], v[164:167], v[188:191], v[36:39]
	v_mfma_f32_16x16x32_bf16 v[28:31], v[172:175], v[188:191], v[28:31]
	v_mfma_f32_16x16x32_bf16 v[20:23], v[164:167], v[196:199], v[20:23]
	v_mfma_f32_16x16x32_bf16 v[12:15], v[172:175], v[196:199], v[12:15]
	v_mfma_f32_16x16x32_bf16 v[4:7], v[164:167], v[206:209], v[4:7]
	v_mfma_f32_16x16x32_bf16 v[0:3], v[172:175], v[206:209], v[0:3]
	v_mfma_f32_16x16x32_bf16 v[52:55], v[168:171], v[184:187], v[52:55]
	v_mfma_f32_16x16x32_bf16 v[44:47], v[176:179], v[184:187], v[44:47]
	v_mfma_f32_16x16x32_bf16 v[36:39], v[168:171], v[192:195], v[36:39]
	v_mfma_f32_16x16x32_bf16 v[28:31], v[176:179], v[192:195], v[28:31]
	v_mfma_f32_16x16x32_bf16 v[20:23], v[168:171], v[202:205], v[20:23]
	v_mfma_f32_16x16x32_bf16 v[12:15], v[176:179], v[202:205], v[12:15]
	v_mfma_f32_16x16x32_bf16 v[4:7], v[168:171], v[210:213], v[4:7]
	v_mfma_f32_16x16x32_bf16 v[0:3], v[176:179], v[210:213], v[0:3]
	s_barrier
	s_add_i32 s78, s78, 2
	s_add_u32 s52, s52, 0x100
	s_addc_u32 s53, s53, 0
	s_add_u32 s76, s76, 0x100
	s_addc_u32 s77, s77, 0
	s_cmp_gt_u32 s78, 41
	s_cbranch_scc0 .LBB0_1018
	s_setprio 0
	s_and_b64 vcc, exec, s[12:13]
	s_cbranch_vccz .LBB0_1021
	s_barrier

.LBB0_1155:
	ds_read_b128 v[144:147], v151
	ds_read_b128 v[154:157], v151 offset:1024
	ds_read_b128 v[158:161], v151 offset:2048
	ds_read_b128 v[162:165], v151 offset:3072
	ds_read_b128 v[166:169], v152
	ds_read_b128 v[170:173], v152 offset:1024
	ds_read_b128 v[174:177], v152 offset:2048
	ds_read_b128 v[178:181], v152 offset:3072
	s_add_u32 s44, s34, 0xfffc0080
	s_addc_u32 s45, s35, -1
	s_cmp_eq_u32 s74, 12
	s_cselect_b32 s51, s15, s45
	s_cselect_b32 s50, s70, s44
	s_cselect_b32 s45, s13, s73
	s_cselect_b32 s44, s71, s72
	v_lshl_add_u64 v[198:199], s[34:35], 0, v[136:137]
	s_add_i32 m0, s58, 0xc000
	ds_read_b128 v[182:185], v153
	ds_read_b128 v[186:189], v153 offset:1024
	ds_read_b128 v[190:193], v153 offset:2048
	ds_read_b128 v[194:197], v153 offset:3072
	ds_read_b128 v[202:205], v153 offset:4096
	ds_read_b128 v[206:209], v153 offset:5120
	ds_read_b128 v[210:213], v153 offset:6144
	ds_read_b128 v[214:217], v153 offset:7168
	global_load_lds_dwordx4 v[198:199], off
	v_lshl_add_u64 v[198:199], s[34:35], 0, v[138:139]
	s_add_i32 m0, s58, 0xe000
	s_nop 0
	global_load_lds_dwordx4 v[198:199], off
	s_waitcnt vmcnt(8)
	s_waitcnt lgkmcnt(0)
	s_barrier
	s_waitcnt lgkmcnt(0)
	v_mfma_f32_16x16x32_bf16 v[124:127], v[144:147], v[182:185], v[124:127]
	v_mfma_f32_16x16x32_bf16 v[120:123], v[158:161], v[182:185], v[120:123]
	v_mfma_f32_16x16x32_bf16 v[116:119], v[144:147], v[190:193], v[116:119]
	v_mfma_f32_16x16x32_bf16 v[108:111], v[158:161], v[190:193], v[108:111]
	v_mfma_f32_16x16x32_bf16 v[100:103], v[144:147], v[202:205], v[100:103]
	v_mfma_f32_16x16x32_bf16 v[92:95], v[158:161], v[202:205], v[92:95]
	v_mfma_f32_16x16x32_bf16 v[84:87], v[144:147], v[210:213], v[84:87]
	v_mfma_f32_16x16x32_bf16 v[76:79], v[158:161], v[210:213], v[76:79]
	v_mfma_f32_16x16x32_bf16 v[124:127], v[154:157], v[186:189], v[124:127]
	v_mfma_f32_16x16x32_bf16 v[120:123], v[162:165], v[186:189], v[120:123]
	v_mfma_f32_16x16x32_bf16 v[116:119], v[154:157], v[194:197], v[116:119]
	v_mfma_f32_16x16x32_bf16 v[108:111], v[162:165], v[194:197], v[108:111]
	v_mfma_f32_16x16x32_bf16 v[100:103], v[154:157], v[206:209], v[100:103]
	v_mfma_f32_16x16x32_bf16 v[92:95], v[162:165], v[206:209], v[92:95]
	v_mfma_f32_16x16x32_bf16 v[84:87], v[154:157], v[214:217], v[84:87]
	v_mfma_f32_16x16x32_bf16 v[76:79], v[162:165], v[214:217], v[76:79]
	v_mfma_f32_16x16x32_bf16 v[112:115], v[166:169], v[182:185], v[112:115]
	v_mfma_f32_16x16x32_bf16 v[104:107], v[174:177], v[182:185], v[104:107]
	v_mfma_f32_16x16x32_bf16 v[96:99], v[166:169], v[190:193], v[96:99]
	v_mfma_f32_16x16x32_bf16 v[88:91], v[174:177], v[190:193], v[88:91]
	v_mfma_f32_16x16x32_bf16 v[80:83], v[166:169], v[202:205], v[80:83]
	v_mfma_f32_16x16x32_bf16 v[72:75], v[174:177], v[202:205], v[72:75]
	v_mfma_f32_16x16x32_bf16 v[68:71], v[166:169], v[210:213], v[68:71]
	v_mfma_f32_16x16x32_bf16 v[64:67], v[174:177], v[210:213], v[64:67]
	v_mfma_f32_16x16x32_bf16 v[112:115], v[170:173], v[186:189], v[112:115]
	v_mfma_f32_16x16x32_bf16 v[104:107], v[178:181], v[186:189], v[104:107]
	v_mfma_f32_16x16x32_bf16 v[96:99], v[170:173], v[194:197], v[96:99]
	v_mfma_f32_16x16x32_bf16 v[88:91], v[178:181], v[194:197], v[88:91]
	v_mfma_f32_16x16x32_bf16 v[80:83], v[170:173], v[206:209], v[80:83]
	v_mfma_f32_16x16x32_bf16 v[72:75], v[178:181], v[206:209], v[72:75]
	v_mfma_f32_16x16x32_bf16 v[68:71], v[170:173], v[214:217], v[68:71]
	v_mfma_f32_16x16x32_bf16 v[64:67], v[178:181], v[214:217], v[64:67]
	s_barrier
	s_add_i32 s75, s65, s55
	v_lshl_add_u64 v[198:199], s[44:45], 0, v[132:133]
	s_mov_b32 m0, s75
	ds_read_b128 v[182:185], v153 offset:16384
	ds_read_b128 v[186:189], v153 offset:17408
	ds_read_b128 v[190:193], v153 offset:18432
	ds_read_b128 v[194:197], v153 offset:19456
	ds_read_b128 v[202:205], v153 offset:20480
	ds_read_b128 v[206:209], v153 offset:21504
	ds_read_b128 v[210:213], v153 offset:22528
	ds_read_b128 v[214:217], v153 offset:23552
	global_load_lds_dwordx4 v[198:199], off
	s_add_i32 m0, s75, 0x2000
	s_add_u32 s76, s44, 0x40000
	v_lshl_add_u64 v[218:219], s[44:45], 0, v[128:129]
	s_addc_u32 s77, s45, 0
	s_add_i32 s75, s66, s55
	global_load_lds_dwordx4 v[218:219], off
	v_lshl_add_u64 v[220:221], s[76:77], 0, v[132:133]
	s_mov_b32 m0, s75
	v_lshl_add_u64 v[222:223], s[50:51], 0, v[130:131]
	global_load_lds_dwordx4 v[220:221], off
	v_lshl_add_u64 v[220:221], s[76:77], 0, v[128:129]
	s_add_i32 m0, s75, 0x2000
	s_nop 0
	global_load_lds_dwordx4 v[220:221], off
	v_lshl_add_u64 v[220:221], s[50:51], 0, v[134:135]
	s_mov_b32 m0, s58
	s_nop 0
	global_load_lds_dwordx4 v[220:221], off
	s_mov_b32 m0, s59
	s_nop 0
	global_load_lds_dwordx4 v[222:223], off
	s_waitcnt vmcnt(8)
	s_waitcnt lgkmcnt(0)
	s_barrier
	s_waitcnt lgkmcnt(0)
	v_mfma_f32_16x16x32_bf16 v[60:63], v[144:147], v[182:185], v[60:63]
	v_mfma_f32_16x16x32_bf16 v[56:59], v[158:161], v[182:185], v[56:59]
	v_mfma_f32_16x16x32_bf16 v[52:55], v[144:147], v[190:193], v[52:55]
	v_mfma_f32_16x16x32_bf16 v[44:47], v[158:161], v[190:193], v[44:47]
	v_mfma_f32_16x16x32_bf16 v[36:39], v[144:147], v[202:205], v[36:39]
	v_mfma_f32_16x16x32_bf16 v[28:31], v[158:161], v[202:205], v[28:31]
	v_mfma_f32_16x16x32_bf16 v[20:23], v[144:147], v[210:213], v[20:23]
	v_mfma_f32_16x16x32_bf16 v[12:15], v[158:161], v[210:213], v[12:15]
	v_mfma_f32_16x16x32_bf16 v[60:63], v[154:157], v[186:189], v[60:63]
	v_mfma_f32_16x16x32_bf16 v[56:59], v[162:165], v[186:189], v[56:59]
	v_mfma_f32_16x16x32_bf16 v[52:55], v[154:157], v[194:197], v[52:55]
	v_mfma_f32_16x16x32_bf16 v[44:47], v[162:165], v[194:197], v[44:47]
	v_mfma_f32_16x16x32_bf16 v[36:39], v[154:157], v[206:209], v[36:39]
	v_mfma_f32_16x16x32_bf16 v[28:31], v[162:165], v[206:209], v[28:31]
	v_mfma_f32_16x16x32_bf16 v[20:23], v[154:157], v[214:217], v[20:23]
	v_mfma_f32_16x16x32_bf16 v[12:15], v[162:165], v[214:217], v[12:15]
	v_mfma_f32_16x16x32_bf16 v[48:51], v[166:169], v[182:185], v[48:51]
	v_mfma_f32_16x16x32_bf16 v[40:43], v[174:177], v[182:185], v[40:43]
	v_mfma_f32_16x16x32_bf16 v[32:35], v[166:169], v[190:193], v[32:35]
	v_mfma_f32_16x16x32_bf16 v[24:27], v[174:177], v[190:193], v[24:27]
	v_mfma_f32_16x16x32_bf16 v[16:19], v[166:169], v[202:205], v[16:19]
	v_mfma_f32_16x16x32_bf16 v[8:11], v[174:177], v[202:205], v[8:11]
	v_mfma_f32_16x16x32_bf16 v[4:7], v[166:169], v[210:213], v[4:7]
	v_mfma_f32_16x16x32_bf16 v[0:3], v[174:177], v[210:213], v[0:3]
	v_mfma_f32_16x16x32_bf16 v[48:51], v[170:173], v[186:189], v[48:51]
	v_mfma_f32_16x16x32_bf16 v[40:43], v[178:181], v[186:189], v[40:43]
	v_mfma_f32_16x16x32_bf16 v[32:35], v[170:173], v[194:197], v[32:35]
	v_mfma_f32_16x16x32_bf16 v[24:27], v[178:181], v[194:197], v[24:27]
	v_mfma_f32_16x16x32_bf16 v[16:19], v[170:173], v[206:209], v[16:19]
	v_mfma_f32_16x16x32_bf16 v[8:11], v[178:181], v[206:209], v[8:11]
	v_mfma_f32_16x16x32_bf16 v[4:7], v[170:173], v[214:217], v[4:7]
	v_mfma_f32_16x16x32_bf16 v[0:3], v[178:181], v[214:217], v[0:3]
	s_barrier
	s_add_i32 s75, 0, 0x18000
	s_add_i32 s76, 0, 0x1c000
	v_add_u32_e32 v162, s75, v149
	v_add_u32_e32 v178, s76, v149
	ds_read_b128 v[144:147], v162
	ds_read_b128 v[154:157], v162 offset:1024
	ds_read_b128 v[158:161], v162 offset:2048
	ds_read_b128 v[162:165], v162 offset:3072
	ds_read_b128 v[166:169], v178
	ds_read_b128 v[170:173], v178 offset:1024
	ds_read_b128 v[174:177], v178 offset:2048
	ds_read_b128 v[178:181], v178 offset:3072
	s_add_u32 s50, s50, 0x40000
	s_addc_u32 s51, s51, 0
	s_mov_b32 m0, s60
	v_lshl_add_u64 v[224:225], s[50:51], 0, v[134:135]
	ds_read_b128 v[182:185], v153 offset:32768
	ds_read_b128 v[186:189], v153 offset:33792
	ds_read_b128 v[190:193], v153 offset:34816
	ds_read_b128 v[194:197], v153 offset:35840
	ds_read_b128 v[202:205], v153 offset:36864
	ds_read_b128 v[206:209], v153 offset:37888
	ds_read_b128 v[210:213], v153 offset:38912
	ds_read_b128 v[214:217], v153 offset:39936
	global_load_lds_dwordx4 v[224:225], off
	v_lshl_add_u64 v[224:225], s[50:51], 0, v[130:131]
	s_mov_b32 m0, s61
	s_nop 0
	global_load_lds_dwordx4 v[224:225], off
	s_waitcnt vmcnt(8)
	s_waitcnt lgkmcnt(0)
	s_barrier
	s_waitcnt lgkmcnt(0)
	v_mfma_f32_16x16x32_bf16 v[124:127], v[144:147], v[182:185], v[124:127]
	v_mfma_f32_16x16x32_bf16 v[120:123], v[158:161], v[182:185], v[120:123]
	v_mfma_f32_16x16x32_bf16 v[116:119], v[144:147], v[190:193], v[116:119]
	v_mfma_f32_16x16x32_bf16 v[108:111], v[158:161], v[190:193], v[108:111]
	v_mfma_f32_16x16x32_bf16 v[100:103], v[144:147], v[202:205], v[100:103]
	v_mfma_f32_16x16x32_bf16 v[92:95], v[158:161], v[202:205], v[92:95]
	v_mfma_f32_16x16x32_bf16 v[84:87], v[144:147], v[210:213], v[84:87]
	v_mfma_f32_16x16x32_bf16 v[76:79], v[158:161], v[210:213], v[76:79]
	v_mfma_f32_16x16x32_bf16 v[124:127], v[154:157], v[186:189], v[124:127]
	v_mfma_f32_16x16x32_bf16 v[120:123], v[162:165], v[186:189], v[120:123]
	v_mfma_f32_16x16x32_bf16 v[116:119], v[154:157], v[194:197], v[116:119]
	v_mfma_f32_16x16x32_bf16 v[108:111], v[162:165], v[194:197], v[108:111]
	v_mfma_f32_16x16x32_bf16 v[100:103], v[154:157], v[206:209], v[100:103]
	v_mfma_f32_16x16x32_bf16 v[92:95], v[162:165], v[206:209], v[92:95]
	v_mfma_f32_16x16x32_bf16 v[84:87], v[154:157], v[214:217], v[84:87]
	v_mfma_f32_16x16x32_bf16 v[76:79], v[162:165], v[214:217], v[76:79]
	v_mfma_f32_16x16x32_bf16 v[112:115], v[166:169], v[182:185], v[112:115]
	v_mfma_f32_16x16x32_bf16 v[104:107], v[174:177], v[182:185], v[104:107]
	v_mfma_f32_16x16x32_bf16 v[96:99], v[166:169], v[190:193], v[96:99]
	v_mfma_f32_16x16x32_bf16 v[88:91], v[174:177], v[190:193], v[88:91]
	v_mfma_f32_16x16x32_bf16 v[80:83], v[166:169], v[202:205], v[80:83]
	v_mfma_f32_16x16x32_bf16 v[72:75], v[174:177], v[202:205], v[72:75]
	v_mfma_f32_16x16x32_bf16 v[68:71], v[166:169], v[210:213], v[68:71]
	v_mfma_f32_16x16x32_bf16 v[64:67], v[174:177], v[210:213], v[64:67]
	v_mfma_f32_16x16x32_bf16 v[112:115], v[170:173], v[186:189], v[112:115]
	v_mfma_f32_16x16x32_bf16 v[104:107], v[178:181], v[186:189], v[104:107]
	v_mfma_f32_16x16x32_bf16 v[96:99], v[170:173], v[194:197], v[96:99]
	v_mfma_f32_16x16x32_bf16 v[88:91], v[178:181], v[194:197], v[88:91]
	v_mfma_f32_16x16x32_bf16 v[80:83], v[170:173], v[206:209], v[80:83]
	v_mfma_f32_16x16x32_bf16 v[72:75], v[178:181], v[206:209], v[72:75]
	v_mfma_f32_16x16x32_bf16 v[68:71], v[170:173], v[214:217], v[68:71]
	v_mfma_f32_16x16x32_bf16 v[64:67], v[178:181], v[214:217], v[64:67]
	s_barrier
	s_add_i32 s50, s75, s55
	v_lshl_add_u64 v[198:199], v[198:199], 0, s[8:9]
	s_mov_b32 m0, s50
	ds_read_b128 v[182:185], v153 offset:49152
	ds_read_b128 v[186:189], v153 offset:50176
	ds_read_b128 v[190:193], v153 offset:51200
	ds_read_b128 v[194:197], v153 offset:52224
	ds_read_b128 v[202:205], v153 offset:53248
	ds_read_b128 v[206:209], v153 offset:54272
	ds_read_b128 v[210:213], v153 offset:55296
	ds_read_b128 v[214:217], v153 offset:56320
	global_load_lds_dwordx4 v[198:199], off
	s_add_i32 m0, s50, 0x2000
	s_add_u32 s44, s44, 0x40080
	v_lshl_add_u64 v[198:199], v[218:219], 0, s[8:9]
	s_addc_u32 s45, s45, 0
	s_add_i32 s50, s76, s55
	global_load_lds_dwordx4 v[198:199], off
	v_lshl_add_u64 v[198:199], s[44:45], 0, v[132:133]
	s_mov_b32 m0, s50
	s_nop 0
	global_load_lds_dwordx4 v[198:199], off
	v_lshl_add_u64 v[198:199], s[44:45], 0, v[128:129]
	s_add_i32 m0, s50, 0x2000
	s_nop 0
	global_load_lds_dwordx4 v[198:199], off
	v_lshl_add_u64 v[198:199], v[220:221], 0, s[8:9]
	s_mov_b32 m0, s63
	s_nop 0
	global_load_lds_dwordx4 v[198:199], off
	v_lshl_add_u64 v[198:199], v[222:223], 0, s[8:9]
	s_mov_b32 m0, s64
	s_nop 0
	global_load_lds_dwordx4 v[198:199], off
	s_waitcnt vmcnt(8)
	s_waitcnt lgkmcnt(0)
	s_barrier
	s_waitcnt lgkmcnt(0)
	v_mfma_f32_16x16x32_bf16 v[60:63], v[144:147], v[182:185], v[60:63]
	v_mfma_f32_16x16x32_bf16 v[56:59], v[158:161], v[182:185], v[56:59]
	v_mfma_f32_16x16x32_bf16 v[52:55], v[144:147], v[190:193], v[52:55]
	v_mfma_f32_16x16x32_bf16 v[44:47], v[158:161], v[190:193], v[44:47]
	v_mfma_f32_16x16x32_bf16 v[36:39], v[144:147], v[202:205], v[36:39]
	v_mfma_f32_16x16x32_bf16 v[28:31], v[158:161], v[202:205], v[28:31]
	v_mfma_f32_16x16x32_bf16 v[20:23], v[144:147], v[210:213], v[20:23]
	v_mfma_f32_16x16x32_bf16 v[12:15], v[158:161], v[210:213], v[12:15]
	v_mfma_f32_16x16x32_bf16 v[60:63], v[154:157], v[186:189], v[60:63]
	v_mfma_f32_16x16x32_bf16 v[56:59], v[162:165], v[186:189], v[56:59]
	v_mfma_f32_16x16x32_bf16 v[52:55], v[154:157], v[194:197], v[52:55]
	v_mfma_f32_16x16x32_bf16 v[44:47], v[162:165], v[194:197], v[44:47]
	v_mfma_f32_16x16x32_bf16 v[36:39], v[154:157], v[206:209], v[36:39]
	v_mfma_f32_16x16x32_bf16 v[28:31], v[162:165], v[206:209], v[28:31]
	v_mfma_f32_16x16x32_bf16 v[20:23], v[154:157], v[214:217], v[20:23]
	v_mfma_f32_16x16x32_bf16 v[12:15], v[162:165], v[214:217], v[12:15]
	v_mfma_f32_16x16x32_bf16 v[48:51], v[166:169], v[182:185], v[48:51]
	v_mfma_f32_16x16x32_bf16 v[40:43], v[174:177], v[182:185], v[40:43]
	v_mfma_f32_16x16x32_bf16 v[32:35], v[166:169], v[190:193], v[32:35]
	v_mfma_f32_16x16x32_bf16 v[24:27], v[174:177], v[190:193], v[24:27]
	v_mfma_f32_16x16x32_bf16 v[16:19], v[166:169], v[202:205], v[16:19]
	v_mfma_f32_16x16x32_bf16 v[8:11], v[174:177], v[202:205], v[8:11]
	v_mfma_f32_16x16x32_bf16 v[4:7], v[166:169], v[210:213], v[4:7]
	v_mfma_f32_16x16x32_bf16 v[0:3], v[174:177], v[210:213], v[0:3]
	v_mfma_f32_16x16x32_bf16 v[48:51], v[170:173], v[186:189], v[48:51]
	v_mfma_f32_16x16x32_bf16 v[40:43], v[178:181], v[186:189], v[40:43]
	v_mfma_f32_16x16x32_bf16 v[32:35], v[170:173], v[194:197], v[32:35]
	v_mfma_f32_16x16x32_bf16 v[24:27], v[178:181], v[194:197], v[24:27]
	v_mfma_f32_16x16x32_bf16 v[16:19], v[170:173], v[206:209], v[16:19]
	v_mfma_f32_16x16x32_bf16 v[8:11], v[178:181], v[206:209], v[8:11]
	v_mfma_f32_16x16x32_bf16 v[4:7], v[170:173], v[214:217], v[4:7]
	v_mfma_f32_16x16x32_bf16 v[0:3], v[178:181], v[214:217], v[0:3]
	s_barrier
	s_add_i32 s74, s74, 2
	s_add_u32 s34, s34, 0x100
	s_addc_u32 s35, s35, 0
	s_add_u32 s72, s72, 0x100
	s_addc_u32 s73, s73, 0
	s_cmp_gt_u32 s74, 13
	s_cbranch_scc0 .LBB0_1155
	s_setprio 0
	s_and_b64 vcc, exec, s[10:11]
	s_cbranch_vccz .LBB0_1158
	s_barrier

.LBB0_1415:
	ds_read_b128 v[140:143], v149
	ds_read_b128 v[152:155], v149 offset:1024
	ds_read_b128 v[156:159], v149 offset:2048
	ds_read_b128 v[160:163], v149 offset:3072
	ds_read_b128 v[164:167], v150
	ds_read_b128 v[168:171], v150 offset:1024
	ds_read_b128 v[172:175], v150 offset:2048
	ds_read_b128 v[176:179], v150 offset:3072
	s_add_u32 s58, s56, 0xfffc0080
	s_addc_u32 s59, s57, -1
	s_cmp_eq_u32 s80, 12
	s_cselect_b32 s61, s51, s59
	s_cselect_b32 s60, s76, s58
	s_cselect_b32 s59, s45, s79
	s_cselect_b32 s58, s77, s78
	v_lshl_add_u64 v[144:145], s[56:57], 0, v[132:133]
	s_add_i32 m0, s65, 0xc000
	ds_read_b128 v[180:183], v151
	ds_read_b128 v[184:187], v151 offset:1024
	ds_read_b128 v[188:191], v151 offset:2048
	ds_read_b128 v[192:195], v151 offset:3072
	ds_read_b128 v[196:199], v151 offset:4096
	ds_read_b128 v[202:205], v151 offset:5120
	ds_read_b128 v[206:209], v151 offset:6144
	ds_read_b128 v[210:213], v151 offset:7168
	global_load_lds_dwordx4 v[144:145], off
	v_lshl_add_u64 v[144:145], s[56:57], 0, v[134:135]
	s_add_i32 m0, s65, 0xe000
	s_nop 0
	global_load_lds_dwordx4 v[144:145], off
	s_waitcnt vmcnt(8)
	s_waitcnt lgkmcnt(0)
	s_barrier
	s_waitcnt lgkmcnt(0)
	v_mfma_f32_16x16x32_bf16 v[124:127], v[140:143], v[180:183], v[124:127]
	v_mfma_f32_16x16x32_bf16 v[120:123], v[156:159], v[180:183], v[120:123]
	v_mfma_f32_16x16x32_bf16 v[112:115], v[140:143], v[188:191], v[112:115]
	v_mfma_f32_16x16x32_bf16 v[104:107], v[156:159], v[188:191], v[104:107]
	v_mfma_f32_16x16x32_bf16 v[96:99], v[140:143], v[196:199], v[96:99]
	v_mfma_f32_16x16x32_bf16 v[88:91], v[156:159], v[196:199], v[88:91]
	v_mfma_f32_16x16x32_bf16 v[80:83], v[140:143], v[206:209], v[80:83]
	v_mfma_f32_16x16x32_bf16 v[72:75], v[156:159], v[206:209], v[72:75]
	v_mfma_f32_16x16x32_bf16 v[124:127], v[152:155], v[184:187], v[124:127]
	v_mfma_f32_16x16x32_bf16 v[120:123], v[160:163], v[184:187], v[120:123]
	v_mfma_f32_16x16x32_bf16 v[112:115], v[152:155], v[192:195], v[112:115]
	v_mfma_f32_16x16x32_bf16 v[104:107], v[160:163], v[192:195], v[104:107]
	v_mfma_f32_16x16x32_bf16 v[96:99], v[152:155], v[202:205], v[96:99]
	v_mfma_f32_16x16x32_bf16 v[88:91], v[160:163], v[202:205], v[88:91]
	v_mfma_f32_16x16x32_bf16 v[80:83], v[152:155], v[210:213], v[80:83]
	v_mfma_f32_16x16x32_bf16 v[72:75], v[160:163], v[210:213], v[72:75]
	v_mfma_f32_16x16x32_bf16 v[116:119], v[164:167], v[180:183], v[116:119]
	v_mfma_f32_16x16x32_bf16 v[108:111], v[172:175], v[180:183], v[108:111]
	v_mfma_f32_16x16x32_bf16 v[100:103], v[164:167], v[188:191], v[100:103]
	v_mfma_f32_16x16x32_bf16 v[92:95], v[172:175], v[188:191], v[92:95]
	v_mfma_f32_16x16x32_bf16 v[84:87], v[164:167], v[196:199], v[84:87]
	v_mfma_f32_16x16x32_bf16 v[76:79], v[172:175], v[196:199], v[76:79]
	v_mfma_f32_16x16x32_bf16 v[68:71], v[164:167], v[206:209], v[68:71]
	v_mfma_f32_16x16x32_bf16 v[64:67], v[172:175], v[206:209], v[64:67]
	v_mfma_f32_16x16x32_bf16 v[116:119], v[168:171], v[184:187], v[116:119]
	v_mfma_f32_16x16x32_bf16 v[108:111], v[176:179], v[184:187], v[108:111]
	v_mfma_f32_16x16x32_bf16 v[100:103], v[168:171], v[192:195], v[100:103]
	v_mfma_f32_16x16x32_bf16 v[92:95], v[176:179], v[192:195], v[92:95]
	v_mfma_f32_16x16x32_bf16 v[84:87], v[168:171], v[202:205], v[84:87]
	v_mfma_f32_16x16x32_bf16 v[76:79], v[176:179], v[202:205], v[76:79]
	v_mfma_f32_16x16x32_bf16 v[68:71], v[168:171], v[210:213], v[68:71]
	v_mfma_f32_16x16x32_bf16 v[64:67], v[176:179], v[210:213], v[64:67]
	s_barrier
	s_add_i32 s81, s74, s64
	v_lshl_add_u64 v[144:145], s[58:59], 0, v[130:131]
	s_mov_b32 m0, s81
	ds_read_b128 v[180:183], v151 offset:16384
	ds_read_b128 v[184:187], v151 offset:17408
	ds_read_b128 v[188:191], v151 offset:18432
	ds_read_b128 v[192:195], v151 offset:19456
	ds_read_b128 v[196:199], v151 offset:20480
	ds_read_b128 v[202:205], v151 offset:21504
	ds_read_b128 v[206:209], v151 offset:22528
	ds_read_b128 v[210:213], v151 offset:23552
	global_load_lds_dwordx4 v[144:145], off
	s_add_i32 m0, s81, 0x2000
	s_add_u32 s82, s58, 0x40000
	v_lshl_add_u64 v[214:215], s[58:59], 0, v[128:129]
	s_addc_u32 s83, s59, 0
	s_add_i32 s81, s75, s64
	global_load_lds_dwordx4 v[214:215], off
	v_lshl_add_u64 v[216:217], s[82:83], 0, v[130:131]
	s_mov_b32 m0, s81
	v_lshl_add_u64 v[218:219], s[60:61], 0, v[128:129]
	global_load_lds_dwordx4 v[216:217], off
	v_lshl_add_u64 v[216:217], s[82:83], 0, v[128:129]
	s_add_i32 m0, s81, 0x2000
	s_nop 0
	global_load_lds_dwordx4 v[216:217], off
	v_lshl_add_u64 v[216:217], s[60:61], 0, v[130:131]
	s_mov_b32 m0, s65
	s_nop 0
	global_load_lds_dwordx4 v[216:217], off
	s_mov_b32 m0, s66
	s_nop 0
	global_load_lds_dwordx4 v[218:219], off
	s_waitcnt vmcnt(8)
	s_waitcnt lgkmcnt(0)
	s_barrier
	s_waitcnt lgkmcnt(0)
	v_mfma_f32_16x16x32_bf16 v[60:63], v[140:143], v[180:183], v[60:63]
	v_mfma_f32_16x16x32_bf16 v[56:59], v[156:159], v[180:183], v[56:59]
	v_mfma_f32_16x16x32_bf16 v[48:51], v[140:143], v[188:191], v[48:51]
	v_mfma_f32_16x16x32_bf16 v[40:43], v[156:159], v[188:191], v[40:43]
	v_mfma_f32_16x16x32_bf16 v[32:35], v[140:143], v[196:199], v[32:35]
	v_mfma_f32_16x16x32_bf16 v[24:27], v[156:159], v[196:199], v[24:27]
	v_mfma_f32_16x16x32_bf16 v[16:19], v[140:143], v[206:209], v[16:19]
	v_mfma_f32_16x16x32_bf16 v[8:11], v[156:159], v[206:209], v[8:11]
	v_mfma_f32_16x16x32_bf16 v[60:63], v[152:155], v[184:187], v[60:63]
	v_mfma_f32_16x16x32_bf16 v[56:59], v[160:163], v[184:187], v[56:59]
	v_mfma_f32_16x16x32_bf16 v[48:51], v[152:155], v[192:195], v[48:51]
	v_mfma_f32_16x16x32_bf16 v[40:43], v[160:163], v[192:195], v[40:43]
	v_mfma_f32_16x16x32_bf16 v[32:35], v[152:155], v[202:205], v[32:35]
	v_mfma_f32_16x16x32_bf16 v[24:27], v[160:163], v[202:205], v[24:27]
	v_mfma_f32_16x16x32_bf16 v[16:19], v[152:155], v[210:213], v[16:19]
	v_mfma_f32_16x16x32_bf16 v[8:11], v[160:163], v[210:213], v[8:11]
	v_mfma_f32_16x16x32_bf16 v[52:55], v[164:167], v[180:183], v[52:55]
	v_mfma_f32_16x16x32_bf16 v[44:47], v[172:175], v[180:183], v[44:47]
	v_mfma_f32_16x16x32_bf16 v[36:39], v[164:167], v[188:191], v[36:39]
	v_mfma_f32_16x16x32_bf16 v[28:31], v[172:175], v[188:191], v[28:31]
	v_mfma_f32_16x16x32_bf16 v[20:23], v[164:167], v[196:199], v[20:23]
	v_mfma_f32_16x16x32_bf16 v[12:15], v[172:175], v[196:199], v[12:15]
	v_mfma_f32_16x16x32_bf16 v[4:7], v[164:167], v[206:209], v[4:7]
	v_mfma_f32_16x16x32_bf16 v[0:3], v[172:175], v[206:209], v[0:3]
	v_mfma_f32_16x16x32_bf16 v[52:55], v[168:171], v[184:187], v[52:55]
	v_mfma_f32_16x16x32_bf16 v[44:47], v[176:179], v[184:187], v[44:47]
	v_mfma_f32_16x16x32_bf16 v[36:39], v[168:171], v[192:195], v[36:39]
	v_mfma_f32_16x16x32_bf16 v[28:31], v[176:179], v[192:195], v[28:31]
	v_mfma_f32_16x16x32_bf16 v[20:23], v[168:171], v[202:205], v[20:23]
	v_mfma_f32_16x16x32_bf16 v[12:15], v[176:179], v[202:205], v[12:15]
	v_mfma_f32_16x16x32_bf16 v[4:7], v[168:171], v[210:213], v[4:7]
	v_mfma_f32_16x16x32_bf16 v[0:3], v[176:179], v[210:213], v[0:3]
	s_barrier
	s_add_i32 s81, 0, 0x18000
	s_add_i32 s82, 0, 0x1c000
	v_add_u32_e32 v160, s81, v147
	v_add_u32_e32 v176, s82, v147
	ds_read_b128 v[140:143], v160
	ds_read_b128 v[152:155], v160 offset:1024
	ds_read_b128 v[156:159], v160 offset:2048
	ds_read_b128 v[160:163], v160 offset:3072
	ds_read_b128 v[164:167], v176
	ds_read_b128 v[168:171], v176 offset:1024
	ds_read_b128 v[172:175], v176 offset:2048
	ds_read_b128 v[176:179], v176 offset:3072
	s_add_u32 s60, s60, 0x40000
	s_addc_u32 s61, s61, 0
	s_mov_b32 m0, s67
	v_lshl_add_u64 v[220:221], s[60:61], 0, v[130:131]
	ds_read_b128 v[180:183], v151 offset:32768
	ds_read_b128 v[184:187], v151 offset:33792
	ds_read_b128 v[188:191], v151 offset:34816
	ds_read_b128 v[192:195], v151 offset:35840
	ds_read_b128 v[196:199], v151 offset:36864
	ds_read_b128 v[202:205], v151 offset:37888
	ds_read_b128 v[206:209], v151 offset:38912
	ds_read_b128 v[210:213], v151 offset:39936
	global_load_lds_dwordx4 v[220:221], off
	v_lshl_add_u64 v[220:221], s[60:61], 0, v[128:129]
	s_mov_b32 m0, s68
	s_nop 0
	global_load_lds_dwordx4 v[220:221], off
	s_waitcnt vmcnt(8)
	s_waitcnt lgkmcnt(0)
	s_barrier
	s_waitcnt lgkmcnt(0)
	v_mfma_f32_16x16x32_bf16 v[124:127], v[140:143], v[180:183], v[124:127]
	v_mfma_f32_16x16x32_bf16 v[120:123], v[156:159], v[180:183], v[120:123]
	v_mfma_f32_16x16x32_bf16 v[112:115], v[140:143], v[188:191], v[112:115]
	v_mfma_f32_16x16x32_bf16 v[104:107], v[156:159], v[188:191], v[104:107]
	v_mfma_f32_16x16x32_bf16 v[96:99], v[140:143], v[196:199], v[96:99]
	v_mfma_f32_16x16x32_bf16 v[88:91], v[156:159], v[196:199], v[88:91]
	v_mfma_f32_16x16x32_bf16 v[80:83], v[140:143], v[206:209], v[80:83]
	v_mfma_f32_16x16x32_bf16 v[72:75], v[156:159], v[206:209], v[72:75]
	v_mfma_f32_16x16x32_bf16 v[124:127], v[152:155], v[184:187], v[124:127]
	v_mfma_f32_16x16x32_bf16 v[120:123], v[160:163], v[184:187], v[120:123]
	v_mfma_f32_16x16x32_bf16 v[112:115], v[152:155], v[192:195], v[112:115]
	v_mfma_f32_16x16x32_bf16 v[104:107], v[160:163], v[192:195], v[104:107]
	v_mfma_f32_16x16x32_bf16 v[96:99], v[152:155], v[202:205], v[96:99]
	v_mfma_f32_16x16x32_bf16 v[88:91], v[160:163], v[202:205], v[88:91]
	v_mfma_f32_16x16x32_bf16 v[80:83], v[152:155], v[210:213], v[80:83]
	v_mfma_f32_16x16x32_bf16 v[72:75], v[160:163], v[210:213], v[72:75]
	v_mfma_f32_16x16x32_bf16 v[116:119], v[164:167], v[180:183], v[116:119]
	v_mfma_f32_16x16x32_bf16 v[108:111], v[172:175], v[180:183], v[108:111]
	v_mfma_f32_16x16x32_bf16 v[100:103], v[164:167], v[188:191], v[100:103]
	v_mfma_f32_16x16x32_bf16 v[92:95], v[172:175], v[188:191], v[92:95]
	v_mfma_f32_16x16x32_bf16 v[84:87], v[164:167], v[196:199], v[84:87]
	v_mfma_f32_16x16x32_bf16 v[76:79], v[172:175], v[196:199], v[76:79]
	v_mfma_f32_16x16x32_bf16 v[68:71], v[164:167], v[206:209], v[68:71]
	v_mfma_f32_16x16x32_bf16 v[64:67], v[172:175], v[206:209], v[64:67]
	v_mfma_f32_16x16x32_bf16 v[116:119], v[168:171], v[184:187], v[116:119]
	v_mfma_f32_16x16x32_bf16 v[108:111], v[176:179], v[184:187], v[108:111]
	v_mfma_f32_16x16x32_bf16 v[100:103], v[168:171], v[192:195], v[100:103]
	v_mfma_f32_16x16x32_bf16 v[92:95], v[176:179], v[192:195], v[92:95]
	v_mfma_f32_16x16x32_bf16 v[84:87], v[168:171], v[202:205], v[84:87]
	v_mfma_f32_16x16x32_bf16 v[76:79], v[176:179], v[202:205], v[76:79]
	v_mfma_f32_16x16x32_bf16 v[68:71], v[168:171], v[210:213], v[68:71]
	v_mfma_f32_16x16x32_bf16 v[64:67], v[176:179], v[210:213], v[64:67]
	s_barrier
	s_add_i32 s60, s81, s64
	v_lshl_add_u64 v[144:145], v[144:145], 0, s[8:9]
	s_mov_b32 m0, s60
	ds_read_b128 v[180:183], v151 offset:49152
	ds_read_b128 v[184:187], v151 offset:50176
	ds_read_b128 v[188:191], v151 offset:51200
	ds_read_b128 v[192:195], v151 offset:52224
	ds_read_b128 v[196:199], v151 offset:53248
	ds_read_b128 v[202:205], v151 offset:54272
	ds_read_b128 v[206:209], v151 offset:55296
	ds_read_b128 v[210:213], v151 offset:56320
	global_load_lds_dwordx4 v[144:145], off
	s_add_i32 m0, s60, 0x2000
	s_add_u32 s58, s58, 0x40080
	v_lshl_add_u64 v[144:145], v[214:215], 0, s[8:9]
	s_addc_u32 s59, s59, 0
	s_add_i32 s60, s82, s64
	global_load_lds_dwordx4 v[144:145], off
	v_lshl_add_u64 v[144:145], s[58:59], 0, v[130:131]
	s_mov_b32 m0, s60
	s_nop 0
	global_load_lds_dwordx4 v[144:145], off
	v_lshl_add_u64 v[144:145], s[58:59], 0, v[128:129]
	s_add_i32 m0, s60, 0x2000
	s_nop 0
	global_load_lds_dwordx4 v[144:145], off
	v_lshl_add_u64 v[144:145], v[216:217], 0, s[8:9]
	s_mov_b32 m0, s70
	s_nop 0
	global_load_lds_dwordx4 v[144:145], off
	v_lshl_add_u64 v[144:145], v[218:219], 0, s[8:9]
	s_mov_b32 m0, s71
	s_nop 0
	global_load_lds_dwordx4 v[144:145], off
	s_waitcnt vmcnt(8)
	s_waitcnt lgkmcnt(0)
	s_barrier
	s_waitcnt lgkmcnt(0)
	v_mfma_f32_16x16x32_bf16 v[60:63], v[140:143], v[180:183], v[60:63]
	v_mfma_f32_16x16x32_bf16 v[56:59], v[156:159], v[180:183], v[56:59]
	v_mfma_f32_16x16x32_bf16 v[48:51], v[140:143], v[188:191], v[48:51]
	v_mfma_f32_16x16x32_bf16 v[40:43], v[156:159], v[188:191], v[40:43]
	v_mfma_f32_16x16x32_bf16 v[32:35], v[140:143], v[196:199], v[32:35]
	v_mfma_f32_16x16x32_bf16 v[24:27], v[156:159], v[196:199], v[24:27]
	v_mfma_f32_16x16x32_bf16 v[16:19], v[140:143], v[206:209], v[16:19]
	v_mfma_f32_16x16x32_bf16 v[8:11], v[156:159], v[206:209], v[8:11]
	v_mfma_f32_16x16x32_bf16 v[60:63], v[152:155], v[184:187], v[60:63]
	v_mfma_f32_16x16x32_bf16 v[56:59], v[160:163], v[184:187], v[56:59]
	v_mfma_f32_16x16x32_bf16 v[48:51], v[152:155], v[192:195], v[48:51]
	v_mfma_f32_16x16x32_bf16 v[40:43], v[160:163], v[192:195], v[40:43]
	v_mfma_f32_16x16x32_bf16 v[32:35], v[152:155], v[202:205], v[32:35]
	v_mfma_f32_16x16x32_bf16 v[24:27], v[160:163], v[202:205], v[24:27]
	v_mfma_f32_16x16x32_bf16 v[16:19], v[152:155], v[210:213], v[16:19]
	v_mfma_f32_16x16x32_bf16 v[8:11], v[160:163], v[210:213], v[8:11]
	v_mfma_f32_16x16x32_bf16 v[52:55], v[164:167], v[180:183], v[52:55]
	v_mfma_f32_16x16x32_bf16 v[44:47], v[172:175], v[180:183], v[44:47]
	v_mfma_f32_16x16x32_bf16 v[36:39], v[164:167], v[188:191], v[36:39]
	v_mfma_f32_16x16x32_bf16 v[28:31], v[172:175], v[188:191], v[28:31]
	v_mfma_f32_16x16x32_bf16 v[20:23], v[164:167], v[196:199], v[20:23]
	v_mfma_f32_16x16x32_bf16 v[12:15], v[172:175], v[196:199], v[12:15]
	v_mfma_f32_16x16x32_bf16 v[4:7], v[164:167], v[206:209], v[4:7]
	v_mfma_f32_16x16x32_bf16 v[0:3], v[172:175], v[206:209], v[0:3]
	v_mfma_f32_16x16x32_bf16 v[52:55], v[168:171], v[184:187], v[52:55]
	v_mfma_f32_16x16x32_bf16 v[44:47], v[176:179], v[184:187], v[44:47]
	v_mfma_f32_16x16x32_bf16 v[36:39], v[168:171], v[192:195], v[36:39]
	v_mfma_f32_16x16x32_bf16 v[28:31], v[176:179], v[192:195], v[28:31]
	v_mfma_f32_16x16x32_bf16 v[20:23], v[168:171], v[202:205], v[20:23]
	v_mfma_f32_16x16x32_bf16 v[12:15], v[176:179], v[202:205], v[12:15]
	v_mfma_f32_16x16x32_bf16 v[4:7], v[168:171], v[210:213], v[4:7]
	v_mfma_f32_16x16x32_bf16 v[0:3], v[176:179], v[210:213], v[0:3]
	s_barrier
	s_add_i32 s80, s80, 2
	s_add_u32 s56, s56, 0x100
	s_addc_u32 s57, s57, 0
	s_add_u32 s78, s78, 0x100
	s_addc_u32 s79, s79, 0
	s_cmp_gt_u32 s80, 13
	s_cbranch_scc0 .LBB0_1415
	s_setprio 0
	s_and_b64 vcc, exec, s[10:11]
	s_cbranch_vccz .LBB0_1418
	s_barrier

.LBB0_1552:
	ds_read_b128 v[64:67], v203
	ds_read_b128 v[68:71], v203 offset:1024
	ds_read_b128 v[72:75], v203 offset:2048
	ds_read_b128 v[76:79], v203 offset:3072
	ds_read_b128 v[80:83], v204
	ds_read_b128 v[84:87], v204 offset:1024
	ds_read_b128 v[88:91], v204 offset:2048
	ds_read_b128 v[92:95], v204 offset:3072
	s_add_u32 s62, s60, 0xfffc0080
	s_addc_u32 s63, s61, -1
	s_cmp_eq_u32 s88, 12
	s_cselect_b32 s65, s55, s63
	s_cselect_b32 s64, s84, s62
	s_cselect_b32 s63, s53, s87
	s_cselect_b32 s62, s85, s86
	v_lshl_add_u64 v[220:221], s[60:61], 0, v[172:173]
	s_add_i32 m0, s71, 0xc000
	ds_read_b128 v[180:183], v205
	ds_read_b128 v[184:187], v205 offset:1024
	ds_read_b128 v[188:191], v205 offset:2048
	ds_read_b128 v[192:195], v205 offset:3072
	ds_read_b128 v[196:199], v205 offset:4096
	ds_read_b128 v[208:211], v205 offset:5120
	ds_read_b128 v[212:215], v205 offset:6144
	ds_read_b128 v[216:219], v205 offset:7168
	global_load_lds_dwordx4 v[220:221], off
	v_lshl_add_u64 v[220:221], s[60:61], 0, v[174:175]
	s_add_i32 m0, s71, 0xe000
	s_nop 0
	global_load_lds_dwordx4 v[220:221], off
	s_waitcnt vmcnt(8)
	s_waitcnt lgkmcnt(0)
	s_barrier
	s_waitcnt lgkmcnt(0)
	v_mfma_f32_16x16x32_bf16 v[148:151], v[64:67], v[180:183], v[148:151]
	v_mfma_f32_16x16x32_bf16 v[144:147], v[72:75], v[180:183], v[144:147]
	v_mfma_f32_16x16x32_bf16 v[132:135], v[64:67], v[188:191], v[132:135]
	v_mfma_f32_16x16x32_bf16 v[128:131], v[72:75], v[188:191], v[128:131]
	v_mfma_f32_16x16x32_bf16 v[116:119], v[64:67], v[196:199], v[116:119]
	v_mfma_f32_16x16x32_bf16 v[112:115], v[72:75], v[196:199], v[112:115]
	v_mfma_f32_16x16x32_bf16 v[104:107], v[64:67], v[212:215], v[104:107]
	v_mfma_f32_16x16x32_bf16 v[100:103], v[72:75], v[212:215], v[100:103]
	v_mfma_f32_16x16x32_bf16 v[148:151], v[68:71], v[184:187], v[148:151]
	v_mfma_f32_16x16x32_bf16 v[144:147], v[76:79], v[184:187], v[144:147]
	v_mfma_f32_16x16x32_bf16 v[132:135], v[68:71], v[192:195], v[132:135]
	v_mfma_f32_16x16x32_bf16 v[128:131], v[76:79], v[192:195], v[128:131]
	v_mfma_f32_16x16x32_bf16 v[116:119], v[68:71], v[208:211], v[116:119]
	v_mfma_f32_16x16x32_bf16 v[112:115], v[76:79], v[208:211], v[112:115]
	v_mfma_f32_16x16x32_bf16 v[104:107], v[68:71], v[216:219], v[104:107]
	v_mfma_f32_16x16x32_bf16 v[100:103], v[76:79], v[216:219], v[100:103]
	v_mfma_f32_16x16x32_bf16 v[152:155], v[80:83], v[180:183], v[152:155]
	v_mfma_f32_16x16x32_bf16 v[156:159], v[88:91], v[180:183], v[156:159]
	v_mfma_f32_16x16x32_bf16 v[136:139], v[80:83], v[188:191], v[136:139]
	v_mfma_f32_16x16x32_bf16 v[140:143], v[88:91], v[188:191], v[140:143]
	v_mfma_f32_16x16x32_bf16 v[120:123], v[80:83], v[196:199], v[120:123]
	v_mfma_f32_16x16x32_bf16 v[124:127], v[88:91], v[196:199], v[124:127]
	v_mfma_f32_16x16x32_bf16 v[96:99], v[80:83], v[212:215], v[96:99]
	v_mfma_f32_16x16x32_bf16 v[108:111], v[88:91], v[212:215], v[108:111]
	v_mfma_f32_16x16x32_bf16 v[152:155], v[84:87], v[184:187], v[152:155]
	v_mfma_f32_16x16x32_bf16 v[156:159], v[92:95], v[184:187], v[156:159]
	v_mfma_f32_16x16x32_bf16 v[136:139], v[84:87], v[192:195], v[136:139]
	v_mfma_f32_16x16x32_bf16 v[140:143], v[92:95], v[192:195], v[140:143]
	v_mfma_f32_16x16x32_bf16 v[120:123], v[84:87], v[208:211], v[120:123]
	v_mfma_f32_16x16x32_bf16 v[124:127], v[92:95], v[208:211], v[124:127]
	v_mfma_f32_16x16x32_bf16 v[96:99], v[84:87], v[216:219], v[96:99]
	v_mfma_f32_16x16x32_bf16 v[108:111], v[92:95], v[216:219], v[108:111]
	s_barrier
	s_add_i32 s89, s80, s70
	v_lshl_add_u64 v[220:221], s[62:63], 0, v[164:165]
	s_mov_b32 m0, s89
	ds_read_b128 v[180:183], v205 offset:16384
	ds_read_b128 v[184:187], v205 offset:17408
	ds_read_b128 v[188:191], v205 offset:18432
	ds_read_b128 v[192:195], v205 offset:19456
	ds_read_b128 v[196:199], v205 offset:20480
	ds_read_b128 v[208:211], v205 offset:21504
	ds_read_b128 v[212:215], v205 offset:22528
	ds_read_b128 v[216:219], v205 offset:23552
	global_load_lds_dwordx4 v[220:221], off
	s_add_i32 m0, s89, 0x2000
	s_add_u32 s90, s62, 0x40000
	v_lshl_add_u64 v[222:223], s[62:63], 0, v[160:161]
	s_addc_u32 s91, s63, 0
	s_add_i32 s89, s81, s70
	global_load_lds_dwordx4 v[222:223], off
	v_lshl_add_u64 v[224:225], s[90:91], 0, v[164:165]
	s_mov_b32 m0, s89
	v_lshl_add_u64 v[226:227], s[64:65], 0, v[162:163]
	global_load_lds_dwordx4 v[224:225], off
	v_lshl_add_u64 v[224:225], s[90:91], 0, v[160:161]
	s_add_i32 m0, s89, 0x2000
	s_nop 0
	global_load_lds_dwordx4 v[224:225], off
	v_lshl_add_u64 v[224:225], s[64:65], 0, v[166:167]
	s_mov_b32 m0, s71
	s_nop 0
	global_load_lds_dwordx4 v[224:225], off
	s_mov_b32 m0, s72
	s_nop 0
	global_load_lds_dwordx4 v[226:227], off
	s_waitcnt vmcnt(8)
	s_waitcnt lgkmcnt(0)
	s_barrier
	s_waitcnt lgkmcnt(0)
	v_mfma_f32_16x16x32_bf16 v[52:55], v[64:67], v[180:183], v[52:55]
	v_mfma_f32_16x16x32_bf16 v[48:51], v[72:75], v[180:183], v[48:51]
	v_mfma_f32_16x16x32_bf16 v[36:39], v[64:67], v[188:191], v[36:39]
	v_mfma_f32_16x16x32_bf16 v[32:35], v[72:75], v[188:191], v[32:35]
	v_mfma_f32_16x16x32_bf16 v[20:23], v[64:67], v[196:199], v[20:23]
	v_mfma_f32_16x16x32_bf16 v[16:19], v[72:75], v[196:199], v[16:19]
	v_mfma_f32_16x16x32_bf16 v[8:11], v[64:67], v[212:215], v[8:11]
	v_mfma_f32_16x16x32_bf16 v[4:7], v[72:75], v[212:215], v[4:7]
	v_mfma_f32_16x16x32_bf16 v[52:55], v[68:71], v[184:187], v[52:55]
	v_mfma_f32_16x16x32_bf16 v[48:51], v[76:79], v[184:187], v[48:51]
	v_mfma_f32_16x16x32_bf16 v[36:39], v[68:71], v[192:195], v[36:39]
	v_mfma_f32_16x16x32_bf16 v[32:35], v[76:79], v[192:195], v[32:35]
	v_mfma_f32_16x16x32_bf16 v[20:23], v[68:71], v[208:211], v[20:23]
	v_mfma_f32_16x16x32_bf16 v[16:19], v[76:79], v[208:211], v[16:19]
	v_mfma_f32_16x16x32_bf16 v[8:11], v[68:71], v[216:219], v[8:11]
	v_mfma_f32_16x16x32_bf16 v[4:7], v[76:79], v[216:219], v[4:7]
	v_mfma_f32_16x16x32_bf16 v[56:59], v[80:83], v[180:183], v[56:59]
	v_mfma_f32_16x16x32_bf16 v[60:63], v[88:91], v[180:183], v[60:63]
	v_mfma_f32_16x16x32_bf16 v[40:43], v[80:83], v[188:191], v[40:43]
	v_mfma_f32_16x16x32_bf16 v[44:47], v[88:91], v[188:191], v[44:47]
	v_mfma_f32_16x16x32_bf16 v[24:27], v[80:83], v[196:199], v[24:27]
	v_mfma_f32_16x16x32_bf16 v[28:31], v[88:91], v[196:199], v[28:31]
	v_mfma_f32_16x16x32_bf16 v[0:3], v[80:83], v[212:215], v[0:3]
	v_mfma_f32_16x16x32_bf16 v[12:15], v[88:91], v[212:215], v[12:15]
	v_mfma_f32_16x16x32_bf16 v[56:59], v[84:87], v[184:187], v[56:59]
	v_mfma_f32_16x16x32_bf16 v[60:63], v[92:95], v[184:187], v[60:63]
	v_mfma_f32_16x16x32_bf16 v[40:43], v[84:87], v[192:195], v[40:43]
	v_mfma_f32_16x16x32_bf16 v[44:47], v[92:95], v[192:195], v[44:47]
	v_mfma_f32_16x16x32_bf16 v[24:27], v[84:87], v[208:211], v[24:27]
	v_mfma_f32_16x16x32_bf16 v[28:31], v[92:95], v[208:211], v[28:31]
	v_mfma_f32_16x16x32_bf16 v[0:3], v[84:87], v[216:219], v[0:3]
	v_mfma_f32_16x16x32_bf16 v[12:15], v[92:95], v[216:219], v[12:15]
	s_barrier
	s_add_i32 s89, 0, 0x18000
	s_add_i32 s90, 0, 0x1c000
	v_add_u32_e32 v76, s89, v201
	v_add_u32_e32 v92, s90, v201
	ds_read_b128 v[64:67], v76
	ds_read_b128 v[68:71], v76 offset:1024
	ds_read_b128 v[72:75], v76 offset:2048
	ds_read_b128 v[76:79], v76 offset:3072
	ds_read_b128 v[80:83], v92
	ds_read_b128 v[84:87], v92 offset:1024
	ds_read_b128 v[88:91], v92 offset:2048
	ds_read_b128 v[92:95], v92 offset:3072
	s_add_u32 s64, s64, 0x40000
	s_addc_u32 s65, s65, 0
	s_mov_b32 m0, s73
	v_lshl_add_u64 v[228:229], s[64:65], 0, v[166:167]
	ds_read_b128 v[180:183], v205 offset:32768
	ds_read_b128 v[184:187], v205 offset:33792
	ds_read_b128 v[188:191], v205 offset:34816
	ds_read_b128 v[192:195], v205 offset:35840
	ds_read_b128 v[196:199], v205 offset:36864
	ds_read_b128 v[208:211], v205 offset:37888
	ds_read_b128 v[212:215], v205 offset:38912
	ds_read_b128 v[216:219], v205 offset:39936
	global_load_lds_dwordx4 v[228:229], off
	v_lshl_add_u64 v[228:229], s[64:65], 0, v[162:163]
	s_mov_b32 m0, s74
	s_nop 0
	global_load_lds_dwordx4 v[228:229], off
	s_waitcnt vmcnt(8)
	s_waitcnt lgkmcnt(0)
	s_barrier
	s_waitcnt lgkmcnt(0)
	v_mfma_f32_16x16x32_bf16 v[148:151], v[64:67], v[180:183], v[148:151]
	v_mfma_f32_16x16x32_bf16 v[144:147], v[72:75], v[180:183], v[144:147]
	v_mfma_f32_16x16x32_bf16 v[132:135], v[64:67], v[188:191], v[132:135]
	v_mfma_f32_16x16x32_bf16 v[128:131], v[72:75], v[188:191], v[128:131]
	v_mfma_f32_16x16x32_bf16 v[116:119], v[64:67], v[196:199], v[116:119]
	v_mfma_f32_16x16x32_bf16 v[112:115], v[72:75], v[196:199], v[112:115]
	v_mfma_f32_16x16x32_bf16 v[104:107], v[64:67], v[212:215], v[104:107]
	v_mfma_f32_16x16x32_bf16 v[100:103], v[72:75], v[212:215], v[100:103]
	v_mfma_f32_16x16x32_bf16 v[148:151], v[68:71], v[184:187], v[148:151]
	v_mfma_f32_16x16x32_bf16 v[144:147], v[76:79], v[184:187], v[144:147]
	v_mfma_f32_16x16x32_bf16 v[132:135], v[68:71], v[192:195], v[132:135]
	v_mfma_f32_16x16x32_bf16 v[128:131], v[76:79], v[192:195], v[128:131]
	v_mfma_f32_16x16x32_bf16 v[116:119], v[68:71], v[208:211], v[116:119]
	v_mfma_f32_16x16x32_bf16 v[112:115], v[76:79], v[208:211], v[112:115]
	v_mfma_f32_16x16x32_bf16 v[104:107], v[68:71], v[216:219], v[104:107]
	v_mfma_f32_16x16x32_bf16 v[100:103], v[76:79], v[216:219], v[100:103]
	v_mfma_f32_16x16x32_bf16 v[152:155], v[80:83], v[180:183], v[152:155]
	v_mfma_f32_16x16x32_bf16 v[156:159], v[88:91], v[180:183], v[156:159]
	v_mfma_f32_16x16x32_bf16 v[136:139], v[80:83], v[188:191], v[136:139]
	v_mfma_f32_16x16x32_bf16 v[140:143], v[88:91], v[188:191], v[140:143]
	v_mfma_f32_16x16x32_bf16 v[120:123], v[80:83], v[196:199], v[120:123]
	v_mfma_f32_16x16x32_bf16 v[124:127], v[88:91], v[196:199], v[124:127]
	v_mfma_f32_16x16x32_bf16 v[96:99], v[80:83], v[212:215], v[96:99]
	v_mfma_f32_16x16x32_bf16 v[108:111], v[88:91], v[212:215], v[108:111]
	v_mfma_f32_16x16x32_bf16 v[152:155], v[84:87], v[184:187], v[152:155]
	v_mfma_f32_16x16x32_bf16 v[156:159], v[92:95], v[184:187], v[156:159]
	v_mfma_f32_16x16x32_bf16 v[136:139], v[84:87], v[192:195], v[136:139]
	v_mfma_f32_16x16x32_bf16 v[140:143], v[92:95], v[192:195], v[140:143]
	v_mfma_f32_16x16x32_bf16 v[120:123], v[84:87], v[208:211], v[120:123]
	v_mfma_f32_16x16x32_bf16 v[124:127], v[92:95], v[208:211], v[124:127]
	v_mfma_f32_16x16x32_bf16 v[96:99], v[84:87], v[216:219], v[96:99]
	v_mfma_f32_16x16x32_bf16 v[108:111], v[92:95], v[216:219], v[108:111]
	s_barrier
	s_add_i32 s64, s89, s70
	v_lshl_add_u64 v[220:221], v[220:221], 0, s[36:37]
	s_mov_b32 m0, s64
	ds_read_b128 v[180:183], v205 offset:49152
	ds_read_b128 v[184:187], v205 offset:50176
	ds_read_b128 v[188:191], v205 offset:51200
	ds_read_b128 v[192:195], v205 offset:52224
	ds_read_b128 v[196:199], v205 offset:53248
	ds_read_b128 v[208:211], v205 offset:54272
	ds_read_b128 v[212:215], v205 offset:55296
	ds_read_b128 v[216:219], v205 offset:56320
	global_load_lds_dwordx4 v[220:221], off
	s_add_i32 m0, s64, 0x2000
	s_add_u32 s62, s62, 0x40080
	v_lshl_add_u64 v[220:221], v[222:223], 0, s[36:37]
	s_addc_u32 s63, s63, 0
	s_add_i32 s64, s90, s70
	global_load_lds_dwordx4 v[220:221], off
	v_lshl_add_u64 v[220:221], s[62:63], 0, v[164:165]
	s_mov_b32 m0, s64
	s_nop 0
	global_load_lds_dwordx4 v[220:221], off
	v_lshl_add_u64 v[220:221], s[62:63], 0, v[160:161]
	s_add_i32 m0, s64, 0x2000
	s_nop 0
	global_load_lds_dwordx4 v[220:221], off
	v_lshl_add_u64 v[220:221], v[224:225], 0, s[36:37]
	s_mov_b32 m0, s76
	s_nop 0
	global_load_lds_dwordx4 v[220:221], off
	v_lshl_add_u64 v[220:221], v[226:227], 0, s[36:37]
	s_mov_b32 m0, s77
	s_nop 0
	global_load_lds_dwordx4 v[220:221], off
	s_waitcnt vmcnt(8)
	s_waitcnt lgkmcnt(0)
	s_barrier
	s_waitcnt lgkmcnt(0)
	v_mfma_f32_16x16x32_bf16 v[52:55], v[64:67], v[180:183], v[52:55]
	v_mfma_f32_16x16x32_bf16 v[48:51], v[72:75], v[180:183], v[48:51]
	v_mfma_f32_16x16x32_bf16 v[36:39], v[64:67], v[188:191], v[36:39]
	v_mfma_f32_16x16x32_bf16 v[32:35], v[72:75], v[188:191], v[32:35]
	v_mfma_f32_16x16x32_bf16 v[20:23], v[64:67], v[196:199], v[20:23]
	v_mfma_f32_16x16x32_bf16 v[16:19], v[72:75], v[196:199], v[16:19]
	v_mfma_f32_16x16x32_bf16 v[8:11], v[64:67], v[212:215], v[8:11]
	v_mfma_f32_16x16x32_bf16 v[4:7], v[72:75], v[212:215], v[4:7]
	v_mfma_f32_16x16x32_bf16 v[52:55], v[68:71], v[184:187], v[52:55]
	v_mfma_f32_16x16x32_bf16 v[48:51], v[76:79], v[184:187], v[48:51]
	v_mfma_f32_16x16x32_bf16 v[36:39], v[68:71], v[192:195], v[36:39]
	v_mfma_f32_16x16x32_bf16 v[32:35], v[76:79], v[192:195], v[32:35]
	v_mfma_f32_16x16x32_bf16 v[20:23], v[68:71], v[208:211], v[20:23]
	v_mfma_f32_16x16x32_bf16 v[16:19], v[76:79], v[208:211], v[16:19]
	v_mfma_f32_16x16x32_bf16 v[8:11], v[68:71], v[216:219], v[8:11]
	v_mfma_f32_16x16x32_bf16 v[4:7], v[76:79], v[216:219], v[4:7]
	v_mfma_f32_16x16x32_bf16 v[56:59], v[80:83], v[180:183], v[56:59]
	v_mfma_f32_16x16x32_bf16 v[60:63], v[88:91], v[180:183], v[60:63]
	v_mfma_f32_16x16x32_bf16 v[40:43], v[80:83], v[188:191], v[40:43]
	v_mfma_f32_16x16x32_bf16 v[44:47], v[88:91], v[188:191], v[44:47]
	v_mfma_f32_16x16x32_bf16 v[24:27], v[80:83], v[196:199], v[24:27]
	v_mfma_f32_16x16x32_bf16 v[28:31], v[88:91], v[196:199], v[28:31]
	v_mfma_f32_16x16x32_bf16 v[0:3], v[80:83], v[212:215], v[0:3]
	v_mfma_f32_16x16x32_bf16 v[12:15], v[88:91], v[212:215], v[12:15]
	v_mfma_f32_16x16x32_bf16 v[56:59], v[84:87], v[184:187], v[56:59]
	v_mfma_f32_16x16x32_bf16 v[60:63], v[92:95], v[184:187], v[60:63]
	v_mfma_f32_16x16x32_bf16 v[40:43], v[84:87], v[192:195], v[40:43]
	v_mfma_f32_16x16x32_bf16 v[44:47], v[92:95], v[192:195], v[44:47]
	v_mfma_f32_16x16x32_bf16 v[24:27], v[84:87], v[208:211], v[24:27]
	v_mfma_f32_16x16x32_bf16 v[28:31], v[92:95], v[208:211], v[28:31]
	v_mfma_f32_16x16x32_bf16 v[0:3], v[84:87], v[216:219], v[0:3]
	v_mfma_f32_16x16x32_bf16 v[12:15], v[92:95], v[216:219], v[12:15]
	s_barrier
	s_add_i32 s88, s88, 2
	s_add_u32 s60, s60, 0x100
	s_addc_u32 s61, s61, 0
	s_add_u32 s86, s86, 0x100
	s_addc_u32 s87, s87, 0
	s_cmp_gt_u32 s88, 13
	s_cbranch_scc0 .LBB0_1552
	s_setprio 0
	s_and_b64 vcc, exec, s[38:39]
	s_cbranch_vccz .LBB0_1555
	s_barrier

.LBB0_1704:
	ds_read_b128 v[140:143], v149
	ds_read_b128 v[152:155], v149 offset:1024
	ds_read_b128 v[156:159], v149 offset:2048
	ds_read_b128 v[160:163], v149 offset:3072
	ds_read_b128 v[164:167], v150
	ds_read_b128 v[168:171], v150 offset:1024
	ds_read_b128 v[172:175], v150 offset:2048
	ds_read_b128 v[176:179], v150 offset:3072
	s_add_u32 s46, s44, 0xfff50080
	s_addc_u32 s47, s45, -1
	s_cmp_eq_u32 s68, 40
	s_cselect_b32 s49, s5, s47
	s_cselect_b32 s48, s4, s46
	s_cselect_b32 s47, s39, s67
	s_cselect_b32 s46, s38, s66
	v_lshl_add_u64 v[144:145], s[44:45], 0, v[132:133]
	s_add_i32 m0, s53, 0xc000
	ds_read_b128 v[180:183], v151
	ds_read_b128 v[184:187], v151 offset:1024
	ds_read_b128 v[188:191], v151 offset:2048
	ds_read_b128 v[192:195], v151 offset:3072
	ds_read_b128 v[196:199], v151 offset:4096
	ds_read_b128 v[202:205], v151 offset:5120
	ds_read_b128 v[206:209], v151 offset:6144
	ds_read_b128 v[210:213], v151 offset:7168
	global_load_lds_dwordx4 v[144:145], off
	v_lshl_add_u64 v[144:145], s[44:45], 0, v[134:135]
	s_add_i32 m0, s53, 0xe000
	s_nop 0
	global_load_lds_dwordx4 v[144:145], off
	s_waitcnt vmcnt(8)
	s_waitcnt lgkmcnt(0)
	s_barrier
	s_waitcnt lgkmcnt(0)
	v_mfma_f32_16x16x32_bf16 v[124:127], v[140:143], v[180:183], v[124:127]
	v_mfma_f32_16x16x32_bf16 v[120:123], v[156:159], v[180:183], v[120:123]
	v_mfma_f32_16x16x32_bf16 v[112:115], v[140:143], v[188:191], v[112:115]
	v_mfma_f32_16x16x32_bf16 v[104:107], v[156:159], v[188:191], v[104:107]
	v_mfma_f32_16x16x32_bf16 v[96:99], v[140:143], v[196:199], v[96:99]
	v_mfma_f32_16x16x32_bf16 v[88:91], v[156:159], v[196:199], v[88:91]
	v_mfma_f32_16x16x32_bf16 v[80:83], v[140:143], v[206:209], v[80:83]
	v_mfma_f32_16x16x32_bf16 v[72:75], v[156:159], v[206:209], v[72:75]
	v_mfma_f32_16x16x32_bf16 v[124:127], v[152:155], v[184:187], v[124:127]
	v_mfma_f32_16x16x32_bf16 v[120:123], v[160:163], v[184:187], v[120:123]
	v_mfma_f32_16x16x32_bf16 v[112:115], v[152:155], v[192:195], v[112:115]
	v_mfma_f32_16x16x32_bf16 v[104:107], v[160:163], v[192:195], v[104:107]
	v_mfma_f32_16x16x32_bf16 v[96:99], v[152:155], v[202:205], v[96:99]
	v_mfma_f32_16x16x32_bf16 v[88:91], v[160:163], v[202:205], v[88:91]
	v_mfma_f32_16x16x32_bf16 v[80:83], v[152:155], v[210:213], v[80:83]
	v_mfma_f32_16x16x32_bf16 v[72:75], v[160:163], v[210:213], v[72:75]
	v_mfma_f32_16x16x32_bf16 v[116:119], v[164:167], v[180:183], v[116:119]
	v_mfma_f32_16x16x32_bf16 v[108:111], v[172:175], v[180:183], v[108:111]
	v_mfma_f32_16x16x32_bf16 v[100:103], v[164:167], v[188:191], v[100:103]
	v_mfma_f32_16x16x32_bf16 v[92:95], v[172:175], v[188:191], v[92:95]
	v_mfma_f32_16x16x32_bf16 v[84:87], v[164:167], v[196:199], v[84:87]
	v_mfma_f32_16x16x32_bf16 v[76:79], v[172:175], v[196:199], v[76:79]
	v_mfma_f32_16x16x32_bf16 v[68:71], v[164:167], v[206:209], v[68:71]
	v_mfma_f32_16x16x32_bf16 v[64:67], v[172:175], v[206:209], v[64:67]
	v_mfma_f32_16x16x32_bf16 v[116:119], v[168:171], v[184:187], v[116:119]
	v_mfma_f32_16x16x32_bf16 v[108:111], v[176:179], v[184:187], v[108:111]
	v_mfma_f32_16x16x32_bf16 v[100:103], v[168:171], v[192:195], v[100:103]
	v_mfma_f32_16x16x32_bf16 v[92:95], v[176:179], v[192:195], v[92:95]
	v_mfma_f32_16x16x32_bf16 v[84:87], v[168:171], v[202:205], v[84:87]
	v_mfma_f32_16x16x32_bf16 v[76:79], v[176:179], v[202:205], v[76:79]
	v_mfma_f32_16x16x32_bf16 v[68:71], v[168:171], v[210:213], v[68:71]
	v_mfma_f32_16x16x32_bf16 v[64:67], v[176:179], v[210:213], v[64:67]
	s_barrier
	s_add_i32 s69, s62, s52
	v_lshl_add_u64 v[144:145], s[46:47], 0, v[130:131]
	s_mov_b32 m0, s69
	ds_read_b128 v[180:183], v151 offset:16384
	ds_read_b128 v[184:187], v151 offset:17408
	ds_read_b128 v[188:191], v151 offset:18432
	ds_read_b128 v[192:195], v151 offset:19456
	ds_read_b128 v[196:199], v151 offset:20480
	ds_read_b128 v[202:205], v151 offset:21504
	ds_read_b128 v[206:209], v151 offset:22528
	ds_read_b128 v[210:213], v151 offset:23552
	global_load_lds_dwordx4 v[144:145], off
	s_add_i32 m0, s69, 0x2000
	s_add_u32 s70, s46, 0xb0000
	v_lshl_add_u64 v[214:215], s[46:47], 0, v[128:129]
	s_addc_u32 s71, s47, 0
	s_add_i32 s69, s63, s52
	global_load_lds_dwordx4 v[214:215], off
	v_lshl_add_u64 v[216:217], s[70:71], 0, v[130:131]
	s_mov_b32 m0, s69
	v_lshl_add_u64 v[218:219], s[48:49], 0, v[128:129]
	global_load_lds_dwordx4 v[216:217], off
	v_lshl_add_u64 v[216:217], s[70:71], 0, v[128:129]
	s_add_i32 m0, s69, 0x2000
	s_nop 0
	global_load_lds_dwordx4 v[216:217], off
	v_lshl_add_u64 v[216:217], s[48:49], 0, v[130:131]
	s_mov_b32 m0, s53
	s_nop 0
	global_load_lds_dwordx4 v[216:217], off
	s_mov_b32 m0, s54
	s_nop 0
	global_load_lds_dwordx4 v[218:219], off
	s_waitcnt vmcnt(8)
	s_waitcnt lgkmcnt(0)
	s_barrier
	s_waitcnt lgkmcnt(0)
	v_mfma_f32_16x16x32_bf16 v[60:63], v[140:143], v[180:183], v[60:63]
	v_mfma_f32_16x16x32_bf16 v[56:59], v[156:159], v[180:183], v[56:59]
	v_mfma_f32_16x16x32_bf16 v[48:51], v[140:143], v[188:191], v[48:51]
	v_mfma_f32_16x16x32_bf16 v[40:43], v[156:159], v[188:191], v[40:43]
	v_mfma_f32_16x16x32_bf16 v[32:35], v[140:143], v[196:199], v[32:35]
	v_mfma_f32_16x16x32_bf16 v[24:27], v[156:159], v[196:199], v[24:27]
	v_mfma_f32_16x16x32_bf16 v[16:19], v[140:143], v[206:209], v[16:19]
	v_mfma_f32_16x16x32_bf16 v[8:11], v[156:159], v[206:209], v[8:11]
	v_mfma_f32_16x16x32_bf16 v[60:63], v[152:155], v[184:187], v[60:63]
	v_mfma_f32_16x16x32_bf16 v[56:59], v[160:163], v[184:187], v[56:59]
	v_mfma_f32_16x16x32_bf16 v[48:51], v[152:155], v[192:195], v[48:51]
	v_mfma_f32_16x16x32_bf16 v[40:43], v[160:163], v[192:195], v[40:43]
	v_mfma_f32_16x16x32_bf16 v[32:35], v[152:155], v[202:205], v[32:35]
	v_mfma_f32_16x16x32_bf16 v[24:27], v[160:163], v[202:205], v[24:27]
	v_mfma_f32_16x16x32_bf16 v[16:19], v[152:155], v[210:213], v[16:19]
	v_mfma_f32_16x16x32_bf16 v[8:11], v[160:163], v[210:213], v[8:11]
	v_mfma_f32_16x16x32_bf16 v[52:55], v[164:167], v[180:183], v[52:55]
	v_mfma_f32_16x16x32_bf16 v[44:47], v[172:175], v[180:183], v[44:47]
	v_mfma_f32_16x16x32_bf16 v[36:39], v[164:167], v[188:191], v[36:39]
	v_mfma_f32_16x16x32_bf16 v[28:31], v[172:175], v[188:191], v[28:31]
	v_mfma_f32_16x16x32_bf16 v[20:23], v[164:167], v[196:199], v[20:23]
	v_mfma_f32_16x16x32_bf16 v[12:15], v[172:175], v[196:199], v[12:15]
	v_mfma_f32_16x16x32_bf16 v[4:7], v[164:167], v[206:209], v[4:7]
	v_mfma_f32_16x16x32_bf16 v[0:3], v[172:175], v[206:209], v[0:3]
	v_mfma_f32_16x16x32_bf16 v[52:55], v[168:171], v[184:187], v[52:55]
	v_mfma_f32_16x16x32_bf16 v[44:47], v[176:179], v[184:187], v[44:47]
	v_mfma_f32_16x16x32_bf16 v[36:39], v[168:171], v[192:195], v[36:39]
	v_mfma_f32_16x16x32_bf16 v[28:31], v[176:179], v[192:195], v[28:31]
	v_mfma_f32_16x16x32_bf16 v[20:23], v[168:171], v[202:205], v[20:23]
	v_mfma_f32_16x16x32_bf16 v[12:15], v[176:179], v[202:205], v[12:15]
	v_mfma_f32_16x16x32_bf16 v[4:7], v[168:171], v[210:213], v[4:7]
	v_mfma_f32_16x16x32_bf16 v[0:3], v[176:179], v[210:213], v[0:3]
	s_barrier
	s_add_i32 s69, 0, 0x18000
	s_add_i32 s70, 0, 0x1c000
	v_add_u32_e32 v160, s69, v147
	v_add_u32_e32 v176, s70, v147
	ds_read_b128 v[140:143], v160
	ds_read_b128 v[152:155], v160 offset:1024
	ds_read_b128 v[156:159], v160 offset:2048
	ds_read_b128 v[160:163], v160 offset:3072
	ds_read_b128 v[164:167], v176
	ds_read_b128 v[168:171], v176 offset:1024
	ds_read_b128 v[172:175], v176 offset:2048
	ds_read_b128 v[176:179], v176 offset:3072
	s_add_u32 s48, s48, 0xb0000
	s_addc_u32 s49, s49, 0
	s_mov_b32 m0, s55
	v_lshl_add_u64 v[220:221], s[48:49], 0, v[130:131]
	ds_read_b128 v[180:183], v151 offset:32768
	ds_read_b128 v[184:187], v151 offset:33792
	ds_read_b128 v[188:191], v151 offset:34816
	ds_read_b128 v[192:195], v151 offset:35840
	ds_read_b128 v[196:199], v151 offset:36864
	ds_read_b128 v[202:205], v151 offset:37888
	ds_read_b128 v[206:209], v151 offset:38912
	ds_read_b128 v[210:213], v151 offset:39936
	global_load_lds_dwordx4 v[220:221], off
	v_lshl_add_u64 v[220:221], s[48:49], 0, v[128:129]
	s_mov_b32 m0, s56
	s_nop 0
	global_load_lds_dwordx4 v[220:221], off
	s_waitcnt vmcnt(8)
	s_waitcnt lgkmcnt(0)
	s_barrier
	s_waitcnt lgkmcnt(0)
	v_mfma_f32_16x16x32_bf16 v[124:127], v[140:143], v[180:183], v[124:127]
	v_mfma_f32_16x16x32_bf16 v[120:123], v[156:159], v[180:183], v[120:123]
	v_mfma_f32_16x16x32_bf16 v[112:115], v[140:143], v[188:191], v[112:115]
	v_mfma_f32_16x16x32_bf16 v[104:107], v[156:159], v[188:191], v[104:107]
	v_mfma_f32_16x16x32_bf16 v[96:99], v[140:143], v[196:199], v[96:99]
	v_mfma_f32_16x16x32_bf16 v[88:91], v[156:159], v[196:199], v[88:91]
	v_mfma_f32_16x16x32_bf16 v[80:83], v[140:143], v[206:209], v[80:83]
	v_mfma_f32_16x16x32_bf16 v[72:75], v[156:159], v[206:209], v[72:75]
	v_mfma_f32_16x16x32_bf16 v[124:127], v[152:155], v[184:187], v[124:127]
	v_mfma_f32_16x16x32_bf16 v[120:123], v[160:163], v[184:187], v[120:123]
	v_mfma_f32_16x16x32_bf16 v[112:115], v[152:155], v[192:195], v[112:115]
	v_mfma_f32_16x16x32_bf16 v[104:107], v[160:163], v[192:195], v[104:107]
	v_mfma_f32_16x16x32_bf16 v[96:99], v[152:155], v[202:205], v[96:99]
	v_mfma_f32_16x16x32_bf16 v[88:91], v[160:163], v[202:205], v[88:91]
	v_mfma_f32_16x16x32_bf16 v[80:83], v[152:155], v[210:213], v[80:83]
	v_mfma_f32_16x16x32_bf16 v[72:75], v[160:163], v[210:213], v[72:75]
	v_mfma_f32_16x16x32_bf16 v[116:119], v[164:167], v[180:183], v[116:119]
	v_mfma_f32_16x16x32_bf16 v[108:111], v[172:175], v[180:183], v[108:111]
	v_mfma_f32_16x16x32_bf16 v[100:103], v[164:167], v[188:191], v[100:103]
	v_mfma_f32_16x16x32_bf16 v[92:95], v[172:175], v[188:191], v[92:95]
	v_mfma_f32_16x16x32_bf16 v[84:87], v[164:167], v[196:199], v[84:87]
	v_mfma_f32_16x16x32_bf16 v[76:79], v[172:175], v[196:199], v[76:79]
	v_mfma_f32_16x16x32_bf16 v[68:71], v[164:167], v[206:209], v[68:71]
	v_mfma_f32_16x16x32_bf16 v[64:67], v[172:175], v[206:209], v[64:67]
	v_mfma_f32_16x16x32_bf16 v[116:119], v[168:171], v[184:187], v[116:119]
	v_mfma_f32_16x16x32_bf16 v[108:111], v[176:179], v[184:187], v[108:111]
	v_mfma_f32_16x16x32_bf16 v[100:103], v[168:171], v[192:195], v[100:103]
	v_mfma_f32_16x16x32_bf16 v[92:95], v[176:179], v[192:195], v[92:95]
	v_mfma_f32_16x16x32_bf16 v[84:87], v[168:171], v[202:205], v[84:87]
	v_mfma_f32_16x16x32_bf16 v[76:79], v[176:179], v[202:205], v[76:79]
	v_mfma_f32_16x16x32_bf16 v[68:71], v[168:171], v[210:213], v[68:71]
	v_mfma_f32_16x16x32_bf16 v[64:67], v[176:179], v[210:213], v[64:67]
	s_barrier
	s_add_i32 s48, s69, s52
	v_lshl_add_u64 v[144:145], v[144:145], 0, s[10:11]
	s_mov_b32 m0, s48
	ds_read_b128 v[180:183], v151 offset:49152
	ds_read_b128 v[184:187], v151 offset:50176
	ds_read_b128 v[188:191], v151 offset:51200
	ds_read_b128 v[192:195], v151 offset:52224
	ds_read_b128 v[196:199], v151 offset:53248
	ds_read_b128 v[202:205], v151 offset:54272
	ds_read_b128 v[206:209], v151 offset:55296
	ds_read_b128 v[210:213], v151 offset:56320
	global_load_lds_dwordx4 v[144:145], off
	s_add_i32 m0, s48, 0x2000
	s_add_u32 s46, s46, 0xb0080
	v_lshl_add_u64 v[144:145], v[214:215], 0, s[10:11]
	s_addc_u32 s47, s47, 0
	s_add_i32 s48, s70, s52
	global_load_lds_dwordx4 v[144:145], off
	v_lshl_add_u64 v[144:145], s[46:47], 0, v[130:131]
	s_mov_b32 m0, s48
	s_nop 0
	global_load_lds_dwordx4 v[144:145], off
	v_lshl_add_u64 v[144:145], s[46:47], 0, v[128:129]
	s_add_i32 m0, s48, 0x2000
	s_nop 0
	global_load_lds_dwordx4 v[144:145], off
	v_lshl_add_u64 v[144:145], v[216:217], 0, s[10:11]
	s_mov_b32 m0, s58
	s_nop 0
	global_load_lds_dwordx4 v[144:145], off
	v_lshl_add_u64 v[144:145], v[218:219], 0, s[10:11]
	s_mov_b32 m0, s59
	s_nop 0
	global_load_lds_dwordx4 v[144:145], off
	s_waitcnt vmcnt(8)
	s_waitcnt lgkmcnt(0)
	s_barrier
	s_waitcnt lgkmcnt(0)
	v_mfma_f32_16x16x32_bf16 v[60:63], v[140:143], v[180:183], v[60:63]
	v_mfma_f32_16x16x32_bf16 v[56:59], v[156:159], v[180:183], v[56:59]
	v_mfma_f32_16x16x32_bf16 v[48:51], v[140:143], v[188:191], v[48:51]
	v_mfma_f32_16x16x32_bf16 v[40:43], v[156:159], v[188:191], v[40:43]
	v_mfma_f32_16x16x32_bf16 v[32:35], v[140:143], v[196:199], v[32:35]
	v_mfma_f32_16x16x32_bf16 v[24:27], v[156:159], v[196:199], v[24:27]
	v_mfma_f32_16x16x32_bf16 v[16:19], v[140:143], v[206:209], v[16:19]
	v_mfma_f32_16x16x32_bf16 v[8:11], v[156:159], v[206:209], v[8:11]
	v_mfma_f32_16x16x32_bf16 v[60:63], v[152:155], v[184:187], v[60:63]
	v_mfma_f32_16x16x32_bf16 v[56:59], v[160:163], v[184:187], v[56:59]
	v_mfma_f32_16x16x32_bf16 v[48:51], v[152:155], v[192:195], v[48:51]
	v_mfma_f32_16x16x32_bf16 v[40:43], v[160:163], v[192:195], v[40:43]
	v_mfma_f32_16x16x32_bf16 v[32:35], v[152:155], v[202:205], v[32:35]
	v_mfma_f32_16x16x32_bf16 v[24:27], v[160:163], v[202:205], v[24:27]
	v_mfma_f32_16x16x32_bf16 v[16:19], v[152:155], v[210:213], v[16:19]
	v_mfma_f32_16x16x32_bf16 v[8:11], v[160:163], v[210:213], v[8:11]
	v_mfma_f32_16x16x32_bf16 v[52:55], v[164:167], v[180:183], v[52:55]
	v_mfma_f32_16x16x32_bf16 v[44:47], v[172:175], v[180:183], v[44:47]
	v_mfma_f32_16x16x32_bf16 v[36:39], v[164:167], v[188:191], v[36:39]
	v_mfma_f32_16x16x32_bf16 v[28:31], v[172:175], v[188:191], v[28:31]
	v_mfma_f32_16x16x32_bf16 v[20:23], v[164:167], v[196:199], v[20:23]
	v_mfma_f32_16x16x32_bf16 v[12:15], v[172:175], v[196:199], v[12:15]
	v_mfma_f32_16x16x32_bf16 v[4:7], v[164:167], v[206:209], v[4:7]
	v_mfma_f32_16x16x32_bf16 v[0:3], v[172:175], v[206:209], v[0:3]
	v_mfma_f32_16x16x32_bf16 v[52:55], v[168:171], v[184:187], v[52:55]
	v_mfma_f32_16x16x32_bf16 v[44:47], v[176:179], v[184:187], v[44:47]
	v_mfma_f32_16x16x32_bf16 v[36:39], v[168:171], v[192:195], v[36:39]
	v_mfma_f32_16x16x32_bf16 v[28:31], v[176:179], v[192:195], v[28:31]
	v_mfma_f32_16x16x32_bf16 v[20:23], v[168:171], v[202:205], v[20:23]
	v_mfma_f32_16x16x32_bf16 v[12:15], v[176:179], v[202:205], v[12:15]
	v_mfma_f32_16x16x32_bf16 v[4:7], v[168:171], v[210:213], v[4:7]
	v_mfma_f32_16x16x32_bf16 v[0:3], v[176:179], v[210:213], v[0:3]
	s_barrier
	s_add_i32 s68, s68, 2
	s_add_u32 s44, s44, 0x100
	s_addc_u32 s45, s45, 0
	s_add_u32 s66, s66, 0x100
	s_addc_u32 s67, s67, 0
	s_cmp_gt_u32 s68, 41
	s_cbranch_scc0 .LBB0_1704
	s_setprio 0
	s_and_b64 vcc, exec, s[12:13]
	s_cbranch_vccz .LBB0_1707
	s_barrier
